# pointer-advance SALU block moved behind the last MFMA of the k-tile; SGU-item epilogue of the mix phase batched (u / bias loads two batches ahead instead of 32 dependent load-store rounds)
# speedup vs baseline: 1.2693x; 1.0042x over previous
; #define MFMA32(a, b, c) __builtin_amdgcn_mfma_f32_32x32x16_bf16((a), (b), (c), 0, 0, 0)
; DI void gemm256(const char* a_u, unsigned a_voff, size_t astep, const char* b_u, unsigned b_voff, size_t bstep, int nk, char* smem, f32x16 (&acc)[4][2]) {
;     ...
;   for (int kt = 0; kt < nk; ++kt) {
;     const int cur = kt & 1, k2 = (kt + 2 < last) ? kt + 2 : last;
;     const char* S = smem + cur * 2 * T2;
;     char* D = smem + (cur ^ 1) * 2 * T2;
;     const char* an = a_u + (size_t)k2 * 128;
;     const char* bn = b_u + (size_t)k2 * 128;
; #pragma unroll
;     for (int s = 0; s < 4; ++s) {
;       bf16x8 a[4], b[2];
; #pragma unroll
;       for (int mi = 0; mi < 4; ++mi) a[mi] = *(const bf16x8*)(S + aoff + mi * 32 * LROW + s * 32);
; #pragma unroll
;       for (int ni = 0; ni < 2; ++ni) b[ni] = *(const bf16x8*)(S + boff + ni * 32 * LROW + s * 32);
;       *(u32x4*)(D + soff + s * 64 * LROW) = ra[s];
;       *(u32x4*)(D + T2 + soff + s * 64 * LROW) = rb[s];
;       ra[s] = *(const u32x4*)(an + s * astep + a_voff);
;       rb[s] = *(const u32x4*)(bn + s * bstep + b_voff);
; #pragma unroll
;       for (int mi = 0; mi < 4; ++mi)
; #pragma unroll
;         for (int ni = 0; ni < 2; ++ni) acc[mi][ni] = MFMA32(a[mi], b[ni], acc[mi][ni]);
;     }
;     __syncthreads();
;   }
.Lg_inproj_loop:
	s_add_i32 s56, s56, 1
	s_add_u32 m0, s59, 0x8000
	s_nop 0
	global_load_lds_dwordx4 v164, s[54:55]
	global_load_lds_dwordx4 v165, s[54:55] offset:1024
	global_load_lds_dwordx4 v130, s[54:55] offset:2048
	global_load_lds_dwordx4 v131, s[54:55] offset:3072
	s_waitcnt lgkmcnt(0)
	v_mfma_f32_16x16x32_bf16 v[114:117], v[196:199], v[212:215], v[114:117]
	ds_read_b128 v[220:223], v194 offset:2048
	v_mfma_f32_16x16x32_bf16 v[118:121], v[196:199], v[216:219], v[118:121]
	ds_read_b128 v[224:227], v194 offset:6144
	v_mfma_f32_16x16x32_bf16 v[50:53], v[196:199], v[242:245], v[50:53]
	ds_read_b128 v[228:231], v194 offset:10240
	v_mfma_f32_16x16x32_bf16 v[54:57], v[196:199], v[246:249], v[54:57]
	ds_read_b128 v[238:241], v194 offset:14336
	v_mfma_f32_16x16x32_bf16 v[98:101], v[200:203], v[212:215], v[98:101]
	v_mfma_f32_16x16x32_bf16 v[102:105], v[200:203], v[216:219], v[102:105]
	v_mfma_f32_16x16x32_bf16 v[34:37], v[200:203], v[242:245], v[34:37]
	v_mfma_f32_16x16x32_bf16 v[38:41], v[200:203], v[246:249], v[38:41]
	v_mfma_f32_16x16x32_bf16 v[82:85], v[204:207], v[212:215], v[82:85]
	v_mfma_f32_16x16x32_bf16 v[86:89], v[204:207], v[216:219], v[86:89]
	v_mfma_f32_16x16x32_bf16 v[18:21], v[204:207], v[242:245], v[18:21]
	v_mfma_f32_16x16x32_bf16 v[22:25], v[204:207], v[246:249], v[22:25]
	v_mfma_f32_16x16x32_bf16 v[66:69], v[208:211], v[212:215], v[66:69]
	v_mfma_f32_16x16x32_bf16 v[70:73], v[208:211], v[216:219], v[70:73]
	v_mfma_f32_16x16x32_bf16 v[2:5], v[208:211], v[242:245], v[2:5]
	v_mfma_f32_16x16x32_bf16 v[6:9], v[208:211], v[246:249], v[6:9]
	s_add_u32 m0, s58, 0x8000
	s_nop 0
	global_load_lds_dwordx4 v164, s[52:53]
	global_load_lds_dwordx4 v165, s[52:53] offset:1024
	global_load_lds_dwordx4 v130, s[52:53] offset:2048
	global_load_lds_dwordx4 v131, s[52:53] offset:3072
	s_waitcnt lgkmcnt(0)
	v_mfma_f32_16x16x32_bf16 v[122:125], v[220:223], v[212:215], v[122:125]
	ds_read_b128 v[196:199], v195 offset:0
	v_mfma_f32_16x16x32_bf16 v[126:129], v[220:223], v[216:219], v[126:129]
	ds_read_b128 v[140:143], v161 offset:0
	v_mfma_f32_16x16x32_bf16 v[58:61], v[220:223], v[242:245], v[58:61]
	ds_read_b128 v[144:147], v161 offset:2048
	v_mfma_f32_16x16x32_bf16 v[62:65], v[220:223], v[246:249], v[62:65]
	ds_read_b128 v[148:151], v161 offset:4096
	v_mfma_f32_16x16x32_bf16 v[106:109], v[224:227], v[212:215], v[106:109]
	ds_read_b128 v[152:155], v161 offset:6144
	v_mfma_f32_16x16x32_bf16 v[110:113], v[224:227], v[216:219], v[110:113]
	ds_read_b128 v[200:203], v195 offset:4096
	v_mfma_f32_16x16x32_bf16 v[42:45], v[224:227], v[242:245], v[42:45]
	ds_read_b128 v[204:207], v195 offset:8192
	v_mfma_f32_16x16x32_bf16 v[46:49], v[224:227], v[246:249], v[46:49]
	ds_read_b128 v[208:211], v195 offset:12288
	v_mfma_f32_16x16x32_bf16 v[90:93], v[228:231], v[212:215], v[90:93]
	v_mfma_f32_16x16x32_bf16 v[94:97], v[228:231], v[216:219], v[94:97]
	v_mfma_f32_16x16x32_bf16 v[26:29], v[228:231], v[242:245], v[26:29]
	v_mfma_f32_16x16x32_bf16 v[30:33], v[228:231], v[246:249], v[30:33]
	v_mfma_f32_16x16x32_bf16 v[74:77], v[238:241], v[212:215], v[74:77]
	v_mfma_f32_16x16x32_bf16 v[78:81], v[238:241], v[216:219], v[78:81]
	v_mfma_f32_16x16x32_bf16 v[10:13], v[238:241], v[242:245], v[10:13]
	v_mfma_f32_16x16x32_bf16 v[14:17], v[238:241], v[246:249], v[14:17]
	s_waitcnt lgkmcnt(0)
	v_mfma_f32_16x16x32_bf16 v[114:117], v[196:199], v[140:143], v[114:117]
	ds_read_b128 v[220:223], v195 offset:2048
	v_mfma_f32_16x16x32_bf16 v[118:121], v[196:199], v[144:147], v[118:121]
	ds_read_b128 v[224:227], v195 offset:6144
	v_mfma_f32_16x16x32_bf16 v[50:53], v[196:199], v[148:151], v[50:53]
	ds_read_b128 v[228:231], v195 offset:10240
	v_mfma_f32_16x16x32_bf16 v[54:57], v[196:199], v[152:155], v[54:57]
	ds_read_b128 v[238:241], v195 offset:14336
	v_mfma_f32_16x16x32_bf16 v[98:101], v[200:203], v[140:143], v[98:101]
	v_mfma_f32_16x16x32_bf16 v[102:105], v[200:203], v[144:147], v[102:105]
	v_mfma_f32_16x16x32_bf16 v[34:37], v[200:203], v[148:151], v[34:37]
	v_mfma_f32_16x16x32_bf16 v[38:41], v[200:203], v[152:155], v[38:41]
	v_mfma_f32_16x16x32_bf16 v[82:85], v[204:207], v[140:143], v[82:85]
	v_mfma_f32_16x16x32_bf16 v[86:89], v[204:207], v[144:147], v[86:89]
	v_mfma_f32_16x16x32_bf16 v[18:21], v[204:207], v[148:151], v[18:21]
	v_mfma_f32_16x16x32_bf16 v[22:25], v[204:207], v[152:155], v[22:25]
	v_mfma_f32_16x16x32_bf16 v[66:69], v[208:211], v[140:143], v[66:69]
	v_mfma_f32_16x16x32_bf16 v[70:73], v[208:211], v[144:147], v[70:73]
	v_mfma_f32_16x16x32_bf16 v[2:5], v[208:211], v[148:151], v[2:5]
	v_mfma_f32_16x16x32_bf16 v[6:9], v[208:211], v[152:155], v[6:9]
	s_waitcnt lgkmcnt(0)
	v_mfma_f32_16x16x32_bf16 v[122:125], v[220:223], v[140:143], v[122:125]
	v_mfma_f32_16x16x32_bf16 v[126:129], v[220:223], v[144:147], v[126:129]
	v_mfma_f32_16x16x32_bf16 v[58:61], v[220:223], v[148:151], v[58:61]
	v_mfma_f32_16x16x32_bf16 v[62:65], v[220:223], v[152:155], v[62:65]
	v_mfma_f32_16x16x32_bf16 v[106:109], v[224:227], v[140:143], v[106:109]
	v_mfma_f32_16x16x32_bf16 v[110:113], v[224:227], v[144:147], v[110:113]
	v_mfma_f32_16x16x32_bf16 v[42:45], v[224:227], v[148:151], v[42:45]
	v_mfma_f32_16x16x32_bf16 v[46:49], v[224:227], v[152:155], v[46:49]
	v_mfma_f32_16x16x32_bf16 v[90:93], v[228:231], v[140:143], v[90:93]
	v_mfma_f32_16x16x32_bf16 v[94:97], v[228:231], v[144:147], v[94:97]
	v_mfma_f32_16x16x32_bf16 v[26:29], v[228:231], v[148:151], v[26:29]
	v_mfma_f32_16x16x32_bf16 v[30:33], v[228:231], v[152:155], v[30:33]
	v_mfma_f32_16x16x32_bf16 v[74:77], v[238:241], v[140:143], v[74:77]
	v_mfma_f32_16x16x32_bf16 v[78:81], v[238:241], v[144:147], v[78:81]
	v_mfma_f32_16x16x32_bf16 v[10:13], v[238:241], v[148:151], v[10:13]
	v_mfma_f32_16x16x32_bf16 v[14:17], v[238:241], v[152:155], v[14:17]
	s_cmp_lt_u32 s56, s57
	s_cselect_b32 s60, 0x80, 0
	s_add_u32 s52, s52, s60
	s_addc_u32 s53, s53, 0
	s_add_u32 s54, s54, s60
	s_addc_u32 s55, s55, 0
	s_cmp_eq_u32 s56, s63
	s_cselect_b32 s52, s64, s52
	s_cselect_b32 s53, s65, s53
	s_cselect_b32 s54, s66, s54
	s_cselect_b32 s55, s67, s55
	s_waitcnt vmcnt(0)
	s_barrier
; #define MFMA32(a, b, c) __builtin_amdgcn_mfma_f32_32x32x16_bf16((a), (b), (c), 0, 0, 0)
; DI void gemm256(const char* a_u, unsigned a_voff, size_t astep, const char* b_u, unsigned b_voff, size_t bstep, int nk, char* smem, f32x16 (&acc)[4][2]) {
;     ...
;   for (int kt = 0; kt < nk; ++kt) {
;     const int cur = kt & 1, k2 = (kt + 2 < last) ? kt + 2 : last;
;     const char* S = smem + cur * 2 * T2;
;     char* D = smem + (cur ^ 1) * 2 * T2;
;     const char* an = a_u + (size_t)k2 * 128;
;     const char* bn = b_u + (size_t)k2 * 128;
; #pragma unroll
;     for (int s = 0; s < 4; ++s) {
;       bf16x8 a[4], b[2];
; #pragma unroll
;       for (int mi = 0; mi < 4; ++mi) a[mi] = *(const bf16x8*)(S + aoff + mi * 32 * LROW + s * 32);
; #pragma unroll
;       for (int ni = 0; ni < 2; ++ni) b[ni] = *(const bf16x8*)(S + boff + ni * 32 * LROW + s * 32);
;       *(u32x4*)(D + soff + s * 64 * LROW) = ra[s];
;       *(u32x4*)(D + T2 + soff + s * 64 * LROW) = rb[s];
;       ra[s] = *(const u32x4*)(an + s * astep + a_voff);
;       rb[s] = *(const u32x4*)(bn + s * bstep + b_voff);
; #pragma unroll
;       for (int mi = 0; mi < 4; ++mi)
; #pragma unroll
;         for (int ni = 0; ni < 2; ++ni) acc[mi][ni] = MFMA32(a[mi], b[ni], acc[mi][ni]);
;     }
;     __syncthreads();
;   }
	ds_read_b128 v[196:199], v194 offset:32768
	ds_read_b128 v[212:215], v160 offset:32768
	ds_read_b128 v[216:219], v160 offset:34816
	ds_read_b128 v[242:245], v160 offset:36864
	ds_read_b128 v[246:249], v160 offset:38912
	ds_read_b128 v[200:203], v194 offset:36864
	ds_read_b128 v[204:207], v194 offset:40960
	ds_read_b128 v[208:211], v194 offset:45056
	s_add_i32 s56, s56, 1
	s_add_u32 m0, s59, 0x0
	s_nop 0
	global_load_lds_dwordx4 v164, s[54:55]
	global_load_lds_dwordx4 v165, s[54:55] offset:1024
	global_load_lds_dwordx4 v130, s[54:55] offset:2048
	global_load_lds_dwordx4 v131, s[54:55] offset:3072
	s_waitcnt lgkmcnt(0)
	v_mfma_f32_16x16x32_bf16 v[114:117], v[196:199], v[212:215], v[114:117]
	ds_read_b128 v[220:223], v194 offset:34816
	v_mfma_f32_16x16x32_bf16 v[118:121], v[196:199], v[216:219], v[118:121]
	ds_read_b128 v[224:227], v194 offset:38912
	v_mfma_f32_16x16x32_bf16 v[50:53], v[196:199], v[242:245], v[50:53]
	ds_read_b128 v[228:231], v194 offset:43008
	v_mfma_f32_16x16x32_bf16 v[54:57], v[196:199], v[246:249], v[54:57]
	ds_read_b128 v[238:241], v194 offset:47104
	v_mfma_f32_16x16x32_bf16 v[98:101], v[200:203], v[212:215], v[98:101]
	v_mfma_f32_16x16x32_bf16 v[102:105], v[200:203], v[216:219], v[102:105]
	v_mfma_f32_16x16x32_bf16 v[34:37], v[200:203], v[242:245], v[34:37]
	v_mfma_f32_16x16x32_bf16 v[38:41], v[200:203], v[246:249], v[38:41]
	v_mfma_f32_16x16x32_bf16 v[82:85], v[204:207], v[212:215], v[82:85]
	v_mfma_f32_16x16x32_bf16 v[86:89], v[204:207], v[216:219], v[86:89]
	v_mfma_f32_16x16x32_bf16 v[18:21], v[204:207], v[242:245], v[18:21]
	v_mfma_f32_16x16x32_bf16 v[22:25], v[204:207], v[246:249], v[22:25]
	v_mfma_f32_16x16x32_bf16 v[66:69], v[208:211], v[212:215], v[66:69]
	v_mfma_f32_16x16x32_bf16 v[70:73], v[208:211], v[216:219], v[70:73]
	v_mfma_f32_16x16x32_bf16 v[2:5], v[208:211], v[242:245], v[2:5]
	v_mfma_f32_16x16x32_bf16 v[6:9], v[208:211], v[246:249], v[6:9]
	s_add_u32 m0, s58, 0x0
	s_nop 0
	global_load_lds_dwordx4 v164, s[52:53]
	global_load_lds_dwordx4 v165, s[52:53] offset:1024
	global_load_lds_dwordx4 v130, s[52:53] offset:2048
	global_load_lds_dwordx4 v131, s[52:53] offset:3072
	s_waitcnt lgkmcnt(0)
	v_mfma_f32_16x16x32_bf16 v[122:125], v[220:223], v[212:215], v[122:125]
	ds_read_b128 v[196:199], v195 offset:32768
	v_mfma_f32_16x16x32_bf16 v[126:129], v[220:223], v[216:219], v[126:129]
	ds_read_b128 v[140:143], v161 offset:32768
	v_mfma_f32_16x16x32_bf16 v[58:61], v[220:223], v[242:245], v[58:61]
	ds_read_b128 v[144:147], v161 offset:34816
	v_mfma_f32_16x16x32_bf16 v[62:65], v[220:223], v[246:249], v[62:65]
	ds_read_b128 v[148:151], v161 offset:36864
	v_mfma_f32_16x16x32_bf16 v[106:109], v[224:227], v[212:215], v[106:109]
	ds_read_b128 v[152:155], v161 offset:38912
	v_mfma_f32_16x16x32_bf16 v[110:113], v[224:227], v[216:219], v[110:113]
	ds_read_b128 v[200:203], v195 offset:36864
	v_mfma_f32_16x16x32_bf16 v[42:45], v[224:227], v[242:245], v[42:45]
	ds_read_b128 v[204:207], v195 offset:40960
	v_mfma_f32_16x16x32_bf16 v[46:49], v[224:227], v[246:249], v[46:49]
	ds_read_b128 v[208:211], v195 offset:45056
	v_mfma_f32_16x16x32_bf16 v[90:93], v[228:231], v[212:215], v[90:93]
	v_mfma_f32_16x16x32_bf16 v[94:97], v[228:231], v[216:219], v[94:97]
	v_mfma_f32_16x16x32_bf16 v[26:29], v[228:231], v[242:245], v[26:29]
	v_mfma_f32_16x16x32_bf16 v[30:33], v[228:231], v[246:249], v[30:33]
	v_mfma_f32_16x16x32_bf16 v[74:77], v[238:241], v[212:215], v[74:77]
	v_mfma_f32_16x16x32_bf16 v[78:81], v[238:241], v[216:219], v[78:81]
	v_mfma_f32_16x16x32_bf16 v[10:13], v[238:241], v[242:245], v[10:13]
	v_mfma_f32_16x16x32_bf16 v[14:17], v[238:241], v[246:249], v[14:17]
	s_waitcnt lgkmcnt(0)
	v_mfma_f32_16x16x32_bf16 v[114:117], v[196:199], v[140:143], v[114:117]
	ds_read_b128 v[220:223], v195 offset:34816
	v_mfma_f32_16x16x32_bf16 v[118:121], v[196:199], v[144:147], v[118:121]
	ds_read_b128 v[224:227], v195 offset:38912
	v_mfma_f32_16x16x32_bf16 v[50:53], v[196:199], v[148:151], v[50:53]
	ds_read_b128 v[228:231], v195 offset:43008
	v_mfma_f32_16x16x32_bf16 v[54:57], v[196:199], v[152:155], v[54:57]
	ds_read_b128 v[238:241], v195 offset:47104
	v_mfma_f32_16x16x32_bf16 v[98:101], v[200:203], v[140:143], v[98:101]
	v_mfma_f32_16x16x32_bf16 v[102:105], v[200:203], v[144:147], v[102:105]
	v_mfma_f32_16x16x32_bf16 v[34:37], v[200:203], v[148:151], v[34:37]
	v_mfma_f32_16x16x32_bf16 v[38:41], v[200:203], v[152:155], v[38:41]
	v_mfma_f32_16x16x32_bf16 v[82:85], v[204:207], v[140:143], v[82:85]
	v_mfma_f32_16x16x32_bf16 v[86:89], v[204:207], v[144:147], v[86:89]
	v_mfma_f32_16x16x32_bf16 v[18:21], v[204:207], v[148:151], v[18:21]
	v_mfma_f32_16x16x32_bf16 v[22:25], v[204:207], v[152:155], v[22:25]
	v_mfma_f32_16x16x32_bf16 v[66:69], v[208:211], v[140:143], v[66:69]
	v_mfma_f32_16x16x32_bf16 v[70:73], v[208:211], v[144:147], v[70:73]
	v_mfma_f32_16x16x32_bf16 v[2:5], v[208:211], v[148:151], v[2:5]
	v_mfma_f32_16x16x32_bf16 v[6:9], v[208:211], v[152:155], v[6:9]
	s_waitcnt lgkmcnt(0)
	v_mfma_f32_16x16x32_bf16 v[122:125], v[220:223], v[140:143], v[122:125]
	v_mfma_f32_16x16x32_bf16 v[126:129], v[220:223], v[144:147], v[126:129]
	v_mfma_f32_16x16x32_bf16 v[58:61], v[220:223], v[148:151], v[58:61]
	v_mfma_f32_16x16x32_bf16 v[62:65], v[220:223], v[152:155], v[62:65]
	v_mfma_f32_16x16x32_bf16 v[106:109], v[224:227], v[140:143], v[106:109]
	v_mfma_f32_16x16x32_bf16 v[110:113], v[224:227], v[144:147], v[110:113]
	v_mfma_f32_16x16x32_bf16 v[42:45], v[224:227], v[148:151], v[42:45]
	v_mfma_f32_16x16x32_bf16 v[46:49], v[224:227], v[152:155], v[46:49]
	v_mfma_f32_16x16x32_bf16 v[90:93], v[228:231], v[140:143], v[90:93]
	v_mfma_f32_16x16x32_bf16 v[94:97], v[228:231], v[144:147], v[94:97]
	v_mfma_f32_16x16x32_bf16 v[26:29], v[228:231], v[148:151], v[26:29]
	v_mfma_f32_16x16x32_bf16 v[30:33], v[228:231], v[152:155], v[30:33]
	v_mfma_f32_16x16x32_bf16 v[74:77], v[238:241], v[140:143], v[74:77]
	v_mfma_f32_16x16x32_bf16 v[78:81], v[238:241], v[144:147], v[78:81]
	v_mfma_f32_16x16x32_bf16 v[10:13], v[238:241], v[148:151], v[10:13]
	v_mfma_f32_16x16x32_bf16 v[14:17], v[238:241], v[152:155], v[14:17]
	s_cmp_lt_u32 s56, s57
	s_cselect_b32 s60, 0x80, 0
	s_add_u32 s52, s52, s60
	s_addc_u32 s53, s53, 0
	s_add_u32 s54, s54, s60
	s_addc_u32 s55, s55, 0
	s_cmp_eq_u32 s56, s63
	s_cselect_b32 s52, s64, s52
	s_cselect_b32 s53, s65, s53
	s_cselect_b32 s54, s66, s54
	s_cselect_b32 s55, s67, s55
	s_waitcnt vmcnt(0)
	s_barrier
; #define MFMA32(a, b, c) __builtin_amdgcn_mfma_f32_32x32x16_bf16((a), (b), (c), 0, 0, 0)
; DI void gemm256(const char* a_u, unsigned a_voff, size_t astep, const char* b_u, unsigned b_voff, size_t bstep, int nk, char* smem, f32x16 (&acc)[4][2]) {
;     ...
;   for (int kt = 0; kt < nk; ++kt) {
;     const int cur = kt & 1, k2 = (kt + 2 < last) ? kt + 2 : last;
;     const char* S = smem + cur * 2 * T2;
;     char* D = smem + (cur ^ 1) * 2 * T2;
;     const char* an = a_u + (size_t)k2 * 128;
;     const char* bn = b_u + (size_t)k2 * 128;
; #pragma unroll
;     for (int s = 0; s < 4; ++s) {
;       bf16x8 a[4], b[2];
; #pragma unroll
;       for (int mi = 0; mi < 4; ++mi) a[mi] = *(const bf16x8*)(S + aoff + mi * 32 * LROW + s * 32);
; #pragma unroll
;       for (int ni = 0; ni < 2; ++ni) b[ni] = *(const bf16x8*)(S + boff + ni * 32 * LROW + s * 32);
;       *(u32x4*)(D + soff + s * 64 * LROW) = ra[s];
;       *(u32x4*)(D + T2 + soff + s * 64 * LROW) = rb[s];
;       ra[s] = *(const u32x4*)(an + s * astep + a_voff);
;       rb[s] = *(const u32x4*)(bn + s * bstep + b_voff);
; #pragma unroll
;       for (int mi = 0; mi < 4; ++mi)
; #pragma unroll
;         for (int ni = 0; ni < 2; ++ni) acc[mi][ni] = MFMA32(a[mi], b[ni], acc[mi][ni]);
;     }
;     __syncthreads();
;   }
	ds_read_b128 v[196:199], v194 offset:0
	ds_read_b128 v[212:215], v160 offset:0
	ds_read_b128 v[216:219], v160 offset:2048
	ds_read_b128 v[242:245], v160 offset:4096
	ds_read_b128 v[246:249], v160 offset:6144
	ds_read_b128 v[200:203], v194 offset:4096
	ds_read_b128 v[204:207], v194 offset:8192
	ds_read_b128 v[208:211], v194 offset:12288
	s_cmp_lt_u32 s56, s57
	s_cbranch_scc1 .Lg_inproj_loop
	s_waitcnt vmcnt(0) lgkmcnt(0)
	s_nop 7
	s_nop 7
	v_permlane16_swap_b32_e32 v114, v118
	v_permlane16_swap_b32_e32 v115, v119
	v_permlane16_swap_b32_e32 v116, v120
	v_permlane16_swap_b32_e32 v117, v121
	v_permlane16_swap_b32_e32 v122, v126
	v_permlane16_swap_b32_e32 v123, v127
	v_permlane16_swap_b32_e32 v124, v128
	v_permlane16_swap_b32_e32 v125, v129
	v_permlane16_swap_b32_e32 v50, v54
	v_permlane16_swap_b32_e32 v51, v55
	v_permlane16_swap_b32_e32 v52, v56
	v_permlane16_swap_b32_e32 v53, v57
	v_permlane16_swap_b32_e32 v58, v62
	v_permlane16_swap_b32_e32 v59, v63
	v_permlane16_swap_b32_e32 v60, v64
	v_permlane16_swap_b32_e32 v61, v65
	v_permlane16_swap_b32_e32 v98, v102
	v_permlane16_swap_b32_e32 v99, v103
	v_permlane16_swap_b32_e32 v100, v104
	v_permlane16_swap_b32_e32 v101, v105
	v_permlane16_swap_b32_e32 v106, v110
	v_permlane16_swap_b32_e32 v107, v111
	v_permlane16_swap_b32_e32 v108, v112
	v_permlane16_swap_b32_e32 v109, v113
	v_permlane16_swap_b32_e32 v34, v38
	v_permlane16_swap_b32_e32 v35, v39
	v_permlane16_swap_b32_e32 v36, v40
	v_permlane16_swap_b32_e32 v37, v41
	v_permlane16_swap_b32_e32 v42, v46
	v_permlane16_swap_b32_e32 v43, v47
	v_permlane16_swap_b32_e32 v44, v48
	v_permlane16_swap_b32_e32 v45, v49
	v_permlane16_swap_b32_e32 v82, v86
	v_permlane16_swap_b32_e32 v83, v87
	v_permlane16_swap_b32_e32 v84, v88
	v_permlane16_swap_b32_e32 v85, v89
	v_permlane16_swap_b32_e32 v90, v94
	v_permlane16_swap_b32_e32 v91, v95
	v_permlane16_swap_b32_e32 v92, v96
	v_permlane16_swap_b32_e32 v93, v97
	v_permlane16_swap_b32_e32 v18, v22
	v_permlane16_swap_b32_e32 v19, v23
	v_permlane16_swap_b32_e32 v20, v24
	v_permlane16_swap_b32_e32 v21, v25
	v_permlane16_swap_b32_e32 v26, v30
	v_permlane16_swap_b32_e32 v27, v31
	v_permlane16_swap_b32_e32 v28, v32
	v_permlane16_swap_b32_e32 v29, v33
	v_permlane16_swap_b32_e32 v66, v70
	v_permlane16_swap_b32_e32 v67, v71
	v_permlane16_swap_b32_e32 v68, v72
	v_permlane16_swap_b32_e32 v69, v73
	v_permlane16_swap_b32_e32 v74, v78
	v_permlane16_swap_b32_e32 v75, v79
	v_permlane16_swap_b32_e32 v76, v80
	v_permlane16_swap_b32_e32 v77, v81
	v_permlane16_swap_b32_e32 v2, v6
	v_permlane16_swap_b32_e32 v3, v7
	v_permlane16_swap_b32_e32 v4, v8
	v_permlane16_swap_b32_e32 v5, v9
	v_permlane16_swap_b32_e32 v10, v14
	v_permlane16_swap_b32_e32 v11, v15
	v_permlane16_swap_b32_e32 v12, v16
	v_permlane16_swap_b32_e32 v13, v17
	v_permlane32_swap_b32_e32 v114, v118
	v_permlane32_swap_b32_e32 v115, v119
	v_permlane32_swap_b32_e32 v116, v120
	v_permlane32_swap_b32_e32 v117, v121
	v_permlane32_swap_b32_e32 v122, v126
	v_permlane32_swap_b32_e32 v123, v127
	v_permlane32_swap_b32_e32 v124, v128
	v_permlane32_swap_b32_e32 v125, v129
	v_permlane32_swap_b32_e32 v50, v54
	v_permlane32_swap_b32_e32 v51, v55
	v_permlane32_swap_b32_e32 v52, v56
	v_permlane32_swap_b32_e32 v53, v57
	v_permlane32_swap_b32_e32 v58, v62
	v_permlane32_swap_b32_e32 v59, v63
	v_permlane32_swap_b32_e32 v60, v64
	v_permlane32_swap_b32_e32 v61, v65
	v_permlane32_swap_b32_e32 v98, v102
	v_permlane32_swap_b32_e32 v99, v103
	v_permlane32_swap_b32_e32 v100, v104
	v_permlane32_swap_b32_e32 v101, v105
	v_permlane32_swap_b32_e32 v106, v110
	v_permlane32_swap_b32_e32 v107, v111
	v_permlane32_swap_b32_e32 v108, v112
	v_permlane32_swap_b32_e32 v109, v113
	v_permlane32_swap_b32_e32 v34, v38
	v_permlane32_swap_b32_e32 v35, v39
	v_permlane32_swap_b32_e32 v36, v40
	v_permlane32_swap_b32_e32 v37, v41
	v_permlane32_swap_b32_e32 v42, v46
	v_permlane32_swap_b32_e32 v43, v47
	v_permlane32_swap_b32_e32 v44, v48
	v_permlane32_swap_b32_e32 v45, v49
	v_permlane32_swap_b32_e32 v82, v86
	v_permlane32_swap_b32_e32 v83, v87
	v_permlane32_swap_b32_e32 v84, v88
	v_permlane32_swap_b32_e32 v85, v89
	v_permlane32_swap_b32_e32 v90, v94
	v_permlane32_swap_b32_e32 v91, v95
	v_permlane32_swap_b32_e32 v92, v96
	v_permlane32_swap_b32_e32 v93, v97
	v_permlane32_swap_b32_e32 v18, v22
	v_permlane32_swap_b32_e32 v19, v23
	v_permlane32_swap_b32_e32 v20, v24
	v_permlane32_swap_b32_e32 v21, v25
	v_permlane32_swap_b32_e32 v26, v30
	v_permlane32_swap_b32_e32 v27, v31
	v_permlane32_swap_b32_e32 v28, v32
	v_permlane32_swap_b32_e32 v29, v33
	v_permlane32_swap_b32_e32 v66, v70
	v_permlane32_swap_b32_e32 v67, v71
	v_permlane32_swap_b32_e32 v68, v72
	v_permlane32_swap_b32_e32 v69, v73
	v_permlane32_swap_b32_e32 v74, v78
	v_permlane32_swap_b32_e32 v75, v79
	v_permlane32_swap_b32_e32 v76, v80
	v_permlane32_swap_b32_e32 v77, v81
	v_permlane32_swap_b32_e32 v2, v6
	v_permlane32_swap_b32_e32 v3, v7
	v_permlane32_swap_b32_e32 v4, v8
	v_permlane32_swap_b32_e32 v5, v9
	v_permlane32_swap_b32_e32 v10, v14
	v_permlane32_swap_b32_e32 v11, v15
	v_permlane32_swap_b32_e32 v12, v16
	v_permlane32_swap_b32_e32 v13, v17
	s_nop 1
	s_branch .LBB0_195

; #define G_LOAD(RA, RB, KT) { _Pragma("unroll") for (int i = 0; i < 4; ++i) { RA[i] = *(const u32x4*)(ap[i] + (KT) * 64); RB[i] = *(const u32x4*)(bp[i] + (KT) * 64); } }
; #define G_STORE(RA, RB, ST) { char* D_ = smem + (ST) * 2 * TSZ; _Pragma("unroll") for (int i = 0; i < 4; ++i) { *(u32x4*)(D_ + soff + i * 32 * LROW) = RA[i]; *(u32x4*)(D_ + TSZ + soff + i * 32 * LROW) = RB[i]; } }
; DI void gemm_main(const bf16_t* (&ap)[4], const bf16_t* (&bp)[4], int nk, char* smem, f32x16 (&acc)[2][2]) {
;     ...
;   G_LOAD(ra0, rb0, 0);
;   G_LOAD(ra1, rb1, 1);
;   __syncthreads();
;   G_STORE(ra0, rb0, 0);
;   __syncthreads();
;   const int last = nk - 1;
;   for (int kt = 0; kt < nk; kt += 2) {
;     const int k2 = (kt + 2 < last) ? kt + 2 : last, k3 = (kt + 3 < last) ? kt + 3 : last;
;     G_LOAD(ra0, rb0, k2);
;     __builtin_amdgcn_sched_barrier(0);
;     G_COMPUTE(0);
;     G_STORE(ra1, rb1, 1);
;     __syncthreads();
;     G_LOAD(ra1, rb1, k3);
;     __builtin_amdgcn_sched_barrier(0);
;     G_COMPUTE(1);
;     G_STORE(ra0, rb0, 0);
;     __syncthreads();
; DI void mix_phase(const Params& p, int layer, char* smem_blk, char* smem) {
;     ...
;     if (it < nS) {
;       const int g = it & 3, n = c0 + (it >> 2);
;       setup_ptrs(ap, (const bf16_t*)(p.ws + O_SW) + (size_t)(layer * 4 + g) * 16384, 128, 0);
;       setup_ptrs(bp, (const bf16_t*)(p.ws + O_VNT) + (size_t)(g * NCH + n) * 16384, 128, 0);
;       gemm_main(ap, bp, 2, smem, acc);
.LBB0_441:
	s_andn2_b64 vcc, exec, s[0:1]
	s_cbranch_vccnz .LBB0_430
	s_and_b32 s12, s11, 3
	s_lshr_b32 s0, s11, 2
	s_or_b32 s1, s12, s8
	v_mov_b32_e32 v3, v1
	s_add_i32 s0, s0, s6
	s_lshl_b32 s11, s1, 15
	v_readlane_b32 s14, v254, 49
	v_readlane_b32 s15, v254, 50
	s_add_u32 s14, s14, s11
	v_ashrrev_i32_e32 v2, 3, v3
	v_lshlrev_b32_e32 v3, 4, v3
	s_addc_u32 s15, s15, 0
	v_and_b32_e32 v180, 0x70, v3
	v_ashrrev_i32_e32 v3, 31, v2
	v_lshl_add_u64 v[4:5], s[14:15], 0, v[180:181]
	v_lshlrev_b64 v[2:3], 8, v[2:3]
	s_mul_i32 s11, s12, 0x42
	v_lshl_add_u64 v[34:35], v[4:5], 0, v[2:3]
	s_add_i32 s22, s11, s0
	v_mov_b32_e32 v3, v1
	s_lshl_b64 s[14:15], s[22:23], 15
	v_readlane_b32 s16, v254, 2
	v_readlane_b32 s17, v254, 3
	s_add_u32 s14, s16, s14
	v_ashrrev_i32_e32 v2, 3, v3
	v_lshlrev_b32_e32 v3, 4, v3
	s_addc_u32 s15, s17, s15
	v_and_b32_e32 v180, 0x70, v3
	v_ashrrev_i32_e32 v3, 31, v2
	s_movk_i32 s11, 0x2000
	v_lshl_add_u64 v[4:5], s[14:15], 0, v[180:181]
	v_lshlrev_b64 v[2:3], 8, v[2:3]
	v_add_co_u32_e32 v10, vcc, s11, v34
	v_lshl_add_u64 v[36:37], v[4:5], 0, v[2:3]
	s_nop 0
	v_addc_co_u32_e32 v11, vcc, 0, v35, vcc
	v_add_co_u32_e32 v14, vcc, s11, v36
	v_mov_b32_e32 v50, v1
	s_nop 0
	v_addc_co_u32_e32 v15, vcc, 0, v37, vcc
	v_add_co_u32_e32 v18, vcc, s48, v34
	global_load_dwordx4 v[2:5], v[34:35], off
	global_load_dwordx4 v[6:9], v[36:37], off
	v_addc_co_u32_e32 v19, vcc, 0, v35, vcc
	v_add_co_u32_e32 v22, vcc, s48, v36
	global_load_dwordx4 v[10:13], v[10:11], off
	s_nop 0
	global_load_dwordx4 v[14:17], v[14:15], off
	v_addc_co_u32_e32 v23, vcc, 0, v37, vcc
	v_add_co_u32_e32 v26, vcc, s38, v34
	global_load_dwordx4 v[18:21], v[18:19], off
	s_nop 0
	global_load_dwordx4 v[22:25], v[22:23], off
	v_addc_co_u32_e32 v27, vcc, 0, v35, vcc
	v_add_co_u32_e32 v30, vcc, s38, v36
	v_lshrrev_b32_e32 v38, 3, v50
	s_nop 0
	v_addc_co_u32_e32 v31, vcc, 0, v37, vcc
	global_load_dwordx4 v[26:29], v[26:27], off
	s_nop 0
	global_load_dwordx4 v[30:33], v[30:31], off
	v_lshlrev_b32_e32 v39, 4, v50
	v_and_b32_e32 v39, 0x70, v39
	v_mul_lo_u32 v38, v38, s28
	s_mov_b64 s[44:45], 0x6000
	v_add3_u32 v162, v38, v39, s3
	s_mov_b64 s[14:15], 0x2000
	s_mov_b64 s[16:17], 0x4000
	v_lshl_add_u64 v[42:43], v[34:35], 0, s[44:45]
	v_lshl_add_u64 v[38:39], v[34:35], 0, s[14:15]
	v_lshl_add_u64 v[40:41], v[34:35], 0, s[16:17]
	global_load_dwordx4 v[66:69], v[34:35], off offset:128
	global_load_dwordx4 v[70:73], v[38:39], off offset:128
	global_load_dwordx4 v[74:77], v[40:41], off offset:128
	v_lshl_add_u64 v[44:45], v[36:37], 0, s[14:15]
	v_lshl_add_u64 v[46:47], v[36:37], 0, s[16:17]
	v_lshl_add_u64 v[48:49], v[36:37], 0, s[44:45]
	global_load_dwordx4 v[78:81], v[42:43], off offset:128
	global_load_dwordx4 v[82:85], v[36:37], off offset:128
	global_load_dwordx4 v[86:89], v[44:45], off offset:128
	global_load_dwordx4 v[90:93], v[46:47], off offset:128
	global_load_dwordx4 v[94:97], v[48:49], off offset:128
	s_waitcnt vmcnt(63) expcnt(7) lgkmcnt(15)
	s_barrier
	v_add_u32_e32 v110, 0xd800, v162
	s_waitcnt vmcnt(0)
	ds_write_b128 v162, v[2:5]
	ds_write_b128 v162, v[10:13] offset:4608
	ds_write_b128 v162, v[18:21] offset:9216
	ds_write_b128 v162, v[6:9] offset:18432
	ds_write_b128 v162, v[14:17] offset:23040
	ds_write_b128 v162, v[22:25] offset:27648
	ds_write_b128 v162, v[26:29] offset:13824
	ds_write_b128 v162, v[30:33] offset:32256
	s_waitcnt lgkmcnt(0)
	s_barrier
	global_load_dwordx4 v[122:125], v[34:35], off offset:128
	global_load_dwordx4 v[126:129], v[38:39], off offset:128
	global_load_dwordx4 v[130:133], v[36:37], off offset:128
	global_load_dwordx4 v[134:137], v[44:45], off offset:128
	global_load_dwordx4 v[138:141], v[40:41], off offset:128
	global_load_dwordx4 v[142:145], v[42:43], off offset:128
	global_load_dwordx4 v[146:149], v[46:47], off offset:128
	global_load_dwordx4 v[150:153], v[48:49], off offset:128
	v_and_b32_e32 v2, 31, v50
	v_lshrrev_b32_e32 v3, 1, v50
	v_and_or_b32 v2, v3, s21, v2
	v_and_b32_e32 v4, 0x5f, v50
	v_and_b32_e32 v3, 16, v3
	v_mul_u32_u24_e32 v4, 0x90, v4
	v_mul_lo_u32 v2, v2, s28
	v_add3_u32 v163, v2, v3, s3
	v_add3_u32 v164, v4, v3, s3
	ds_read_b128 v[2:5], v163
	ds_read_b128 v[6:9], v164 offset:18432
	ds_read_b128 v[10:13], v164 offset:23040
	s_waitcnt lgkmcnt(1)
	v_mfma_f32_32x32x16_bf16 v[34:49], v[2:5], v[6:9], 0
	s_waitcnt lgkmcnt(0)
	v_mfma_f32_32x32x16_bf16 v[50:65], v[2:5], v[10:13], 0
	ds_read_b128 v[2:5], v163 offset:4608
	ds_read_b128 v[98:101], v163 offset:32
	ds_read_b128 v[102:105], v164 offset:18464
	ds_read_b128 v[106:109], v164 offset:23072
	s_waitcnt lgkmcnt(1)
	v_mfma_f32_32x32x16_bf16 v[34:49], v[98:101], v[102:105], v[34:49]
	s_waitcnt lgkmcnt(0)
	v_mfma_f32_32x32x16_bf16 v[50:65], v[98:101], v[106:109], v[50:65]
	ds_read_b128 v[98:101], v163 offset:4640
	v_mfma_f32_32x32x16_bf16 v[18:33], v[2:5], v[6:9], 0
	v_mfma_f32_32x32x16_bf16 v[2:17], v[2:5], v[10:13], 0
	s_waitcnt lgkmcnt(0)
	v_mfma_f32_32x32x16_bf16 v[18:33], v[98:101], v[102:105], v[18:33]
	v_mfma_f32_32x32x16_bf16 v[2:17], v[98:101], v[106:109], v[2:17]
	ds_read_b128 v[98:101], v163 offset:64
	ds_read_b128 v[102:105], v164 offset:18496
	ds_read_b128 v[106:109], v164 offset:23104
	s_waitcnt lgkmcnt(1)
	v_mfma_f32_32x32x16_bf16 v[34:49], v[98:101], v[102:105], v[34:49]
	s_waitcnt lgkmcnt(0)
	v_mfma_f32_32x32x16_bf16 v[50:65], v[98:101], v[106:109], v[50:65]
	ds_read_b128 v[98:101], v163 offset:4672
	s_waitcnt lgkmcnt(0)
	v_mfma_f32_32x32x16_bf16 v[18:33], v[98:101], v[102:105], v[18:33]
	v_mfma_f32_32x32x16_bf16 v[2:17], v[98:101], v[106:109], v[2:17]
	ds_read_b128 v[98:101], v163 offset:96
	ds_read_b128 v[102:105], v164 offset:18528
	ds_read_b128 v[106:109], v164 offset:23136
	s_waitcnt lgkmcnt(1)
	v_mfma_f32_32x32x16_bf16 v[34:49], v[98:101], v[102:105], v[34:49]
	s_waitcnt lgkmcnt(0)
	v_mfma_f32_32x32x16_bf16 v[50:65], v[98:101], v[106:109], v[50:65]
	ds_read_b128 v[98:101], v163 offset:4704
	ds_write_b128 v162, v[66:69] offset:36864
	ds_write_b128 v162, v[82:85] offset:55296
	ds_write_b128 v162, v[70:73] offset:41472
	ds_write_b128 v162, v[86:89] offset:59904
	ds_write_b128 v162, v[74:77] offset:46080
	ds_write_b128 v162, v[90:93] offset:64512
	ds_write_b128 v162, v[78:81] offset:50688
	ds_write_b128 v110, v[94:97] offset:13824
	s_waitcnt lgkmcnt(0)
	s_barrier
; #define G_LOAD(RA, RB, KT) { _Pragma("unroll") for (int i = 0; i < 4; ++i) { RA[i] = *(const u32x4*)(ap[i] + (KT) * 64); RB[i] = *(const u32x4*)(bp[i] + (KT) * 64); } }
; #define G_STORE(RA, RB, ST) { char* D_ = smem + (ST) * 2 * TSZ; _Pragma("unroll") for (int i = 0; i < 4; ++i) { *(u32x4*)(D_ + soff + i * 32 * LROW) = RA[i]; *(u32x4*)(D_ + TSZ + soff + i * 32 * LROW) = RB[i]; } }
; DI void gemm_main(const bf16_t* (&ap)[4], const bf16_t* (&bp)[4], int nk, char* smem, f32x16 (&acc)[2][2]) {
;     ...
;     G_LOAD(ra1, rb1, k3);
;     __builtin_amdgcn_sched_barrier(0);
;     G_COMPUTE(1);
;     G_STORE(ra0, rb0, 0);
;     __syncthreads();
; DI void mix_phase(const Params& p, int layer, char* smem_blk, char* smem) {
;     ...
;       const bf16_t* U = (const bf16_t*)(p.ws + O_U);
;       bf16_t* Y = (bf16_t*)(p.ws + O_Y);
;       const float* sb = p.sgu_b + (layer * 4 + g) * 128;
; #pragma unroll
;       for (int mi = 0; mi < 2; ++mi)
; #pragma unroll
;         for (int ni = 0; ni < 2; ++ni)
; #pragma unroll
;           for (int reg = 0; reg < 16; ++reg) {
;             const int ii = 64 * wm + 32 * mi + (reg & 3) + 8 * (reg >> 2) + 4 * h, cc = 64 * wn + 32 * ni + r;
;             const size_t tok = (size_t)n * 128 + ii;
;             const unsigned uu = U[tok * 512 + g * 128 + cc];
;             const float uf = __uint_as_float(uu << 16);
;             Y[tok * DM + g * 128 + cc] = f2bf(uf * (acc[mi][ni][reg] + sb[ii]));
;           }
	v_mfma_f32_32x32x16_bf16 v[18:33], v[98:101], v[102:105], v[18:33]
	v_mfma_f32_32x32x16_bf16 v[2:17], v[98:101], v[106:109], v[2:17]
	ds_read_b128 v[70:73], v163 offset:36864
	ds_read_b128 v[110:113], v164 offset:55296
	ds_read_b128 v[154:157], v163 offset:36896
	ds_read_b128 v[82:85], v164 offset:55328
	s_lshl_b32 s22, s1, 7
	v_readlane_b32 s52, v252, 2
	s_lshl_b64 s[14:15], s[22:23], 2
	v_readlane_b32 s54, v252, 4
	v_readlane_b32 s55, v252, 5
	s_add_u32 s14, s54, s14
	v_lshlrev_b32_e32 v121, 6, v121
	s_mov_b32 s1, s23
	s_waitcnt lgkmcnt(2)
	v_mfma_f32_32x32x16_bf16 v[34:49], v[70:73], v[110:113], v[34:49]
	ds_read_b128 v[102:105], v163 offset:41472
	ds_read_b128 v[90:93], v163 offset:41504
	ds_read_b128 v[106:109], v164 offset:59904
	ds_read_b128 v[94:97], v164 offset:59936
	ds_read_b128 v[158:161], v163 offset:36928
	ds_read_b128 v[114:117], v163 offset:36960
	ds_read_b128 v[78:81], v163 offset:41536
	ds_read_b128 v[66:69], v163 offset:41568
	s_addc_u32 s15, s55, s15
	s_lshl_b64 s[0:1], s[0:1], 7
	s_lshl_b32 s11, s12, 8
	v_readlane_b32 s12, v254, 4
	v_readlane_b32 s13, v254, 5
	s_add_u32 s12, s12, s11
	s_waitcnt lgkmcnt(5)
	v_mfma_f32_32x32x16_bf16 v[50:65], v[70:73], v[106:109], v[50:65]
	ds_read_b128 v[98:101], v164 offset:55360
	ds_read_b128 v[74:77], v164 offset:55392
	ds_read_b128 v[86:89], v164 offset:59968
	ds_read_b128 v[70:73], v164 offset:60000
	s_waitcnt vmcnt(7)
	ds_write_b128 v162, v[122:125]
	s_waitcnt vmcnt(5)
	ds_write_b128 v162, v[130:133] offset:18432
	ds_write_b128 v162, v[126:129] offset:4608
	s_waitcnt vmcnt(4)
	ds_write_b128 v162, v[134:137] offset:23040
	v_lshl_or_b32 v124, v118, 2, v121
	v_lshlrev_b32_e32 v120, 1, v120
	v_ashrrev_i32_e32 v125, 31, v124
	s_addc_u32 s13, s13, 0
	v_lshl_or_b32 v180, v119, 7, v120
	v_lshl_add_u64 v[128:129], s[0:1], 0, v[124:125]
	v_lshl_add_u64 v[122:123], s[12:13], 0, v[180:181]
	v_lshlrev_b64 v[130:131], 10, v[128:129]
	v_lshl_add_u64 v[126:127], v[124:125], 2, s[14:15]
	s_waitcnt vmcnt(3)
	ds_write_b128 v162, v[138:141] offset:9216
	s_waitcnt vmcnt(1)
	ds_write_b128 v162, v[146:149] offset:27648
	ds_write_b128 v162, v[142:145] offset:13824
	s_waitcnt vmcnt(0)
	ds_write_b128 v162, v[150:153] offset:32256
	s_waitcnt lgkmcnt(0)
	s_barrier
	v_mfma_f32_32x32x16_bf16 v[34:49], v[154:157], v[82:85], v[34:49]
	v_mfma_f32_32x32x16_bf16 v[50:65], v[154:157], v[94:97], v[50:65]
	v_mfma_f32_32x32x16_bf16 v[34:49], v[158:161], v[98:101], v[34:49]
	v_mfma_f32_32x32x16_bf16 v[50:65], v[158:161], v[86:89], v[50:65]
	v_mfma_f32_32x32x16_bf16 v[34:49], v[114:117], v[74:77], v[34:49]
	v_mfma_f32_32x32x16_bf16 v[50:65], v[114:117], v[70:73], v[50:65]
	v_mfma_f32_32x32x16_bf16 v[18:33], v[102:105], v[110:113], v[18:33]
	v_mfma_f32_32x32x16_bf16 v[2:17], v[102:105], v[106:109], v[2:17]
	v_mfma_f32_32x32x16_bf16 v[18:33], v[90:93], v[82:85], v[18:33]
	v_mfma_f32_32x32x16_bf16 v[2:17], v[90:93], v[94:97], v[2:17]
	v_mfma_f32_32x32x16_bf16 v[18:33], v[78:81], v[98:101], v[18:33]
	v_mfma_f32_32x32x16_bf16 v[2:17], v[78:81], v[86:89], v[2:17]
	v_mfma_f32_32x32x16_bf16 v[18:33], v[66:69], v[74:77], v[18:33]
	v_mfma_f32_32x32x16_bf16 v[2:17], v[66:69], v[70:73], v[2:17]
	v_readlane_b32 s54, v254, 4
	v_readlane_b32 s55, v254, 5
	s_lshl_b64 s[52:53], s[0:1], 10
	s_add_u32 s54, s54, s11
	s_addc_u32 s55, s55, 0
	s_add_u32 s52, s52, s54
	s_addc_u32 s53, s53, s55
	v_readlane_b32 s12, v254, 20
	s_nop 0
	s_add_u32 s12, s12, s11
	v_readlane_b32 s11, v254, 21
	s_nop 0
	s_addc_u32 s13, s11, 0
	s_lshl_b64 s[56:57], s[0:1], 12
	s_add_u32 s56, s56, s12
	s_addc_u32 s57, s57, s13
	v_lshl_add_u32 v193, v124, 10, v180
	v_lshl_add_u32 v194, v124, 12, v180
	v_add_u32_e32 v195, 0x1000, v194
	v_add_u32_e32 v196, 0x2000, v194
	v_add_u32_e32 v197, 0x3000, v194
	global_load_dwordx4 v[206:209], v[126:127], off offset:0
	global_load_dwordx4 v[210:213], v[126:127], off offset:32
	s_add_u32 s58, s52, 0x0
	s_addc_u32 s59, s53, 0
	global_load_ushort v66, v193, s[58:59]
	global_load_ushort v67, v193, s[58:59] offset:64
	global_load_ushort v68, v193, s[58:59] offset:1024
	global_load_ushort v69, v193, s[58:59] offset:1088
	global_load_ushort v70, v193, s[58:59] offset:2048
	global_load_ushort v71, v193, s[58:59] offset:2112
	global_load_ushort v72, v193, s[58:59] offset:3072
	global_load_ushort v73, v193, s[58:59] offset:3136
	s_add_u32 s58, s52, 0x2000
	s_addc_u32 s59, s53, 0
	global_load_ushort v74, v193, s[58:59]
	global_load_ushort v75, v193, s[58:59] offset:64
	global_load_ushort v76, v193, s[58:59] offset:1024
	global_load_ushort v77, v193, s[58:59] offset:1088
	global_load_ushort v78, v193, s[58:59] offset:2048
	global_load_ushort v79, v193, s[58:59] offset:2112
	global_load_ushort v80, v193, s[58:59] offset:3072
	global_load_ushort v81, v193, s[58:59] offset:3136
	global_load_dwordx4 v[214:217], v[126:127], off offset:64
	global_load_dwordx4 v[218:221], v[126:127], off offset:96
	s_add_u32 s58, s52, 0x4000
	s_addc_u32 s59, s53, 0
	global_load_ushort v82, v193, s[58:59]
	global_load_ushort v83, v193, s[58:59] offset:64
	global_load_ushort v84, v193, s[58:59] offset:1024
	global_load_ushort v85, v193, s[58:59] offset:1088
	global_load_ushort v86, v193, s[58:59] offset:2048
	global_load_ushort v87, v193, s[58:59] offset:2112
	global_load_ushort v88, v193, s[58:59] offset:3072
	global_load_ushort v89, v193, s[58:59] offset:3136
	s_add_u32 s58, s52, 0x6000
	s_addc_u32 s59, s53, 0
	global_load_ushort v90, v193, s[58:59]
	global_load_ushort v91, v193, s[58:59] offset:64
	global_load_ushort v92, v193, s[58:59] offset:1024
	global_load_ushort v93, v193, s[58:59] offset:1088
	global_load_ushort v94, v193, s[58:59] offset:2048
	global_load_ushort v95, v193, s[58:59] offset:2112
	global_load_ushort v96, v193, s[58:59] offset:3072
	global_load_ushort v97, v193, s[58:59] offset:3136
	s_waitcnt vmcnt(18)
; DI void mix_phase(const Params& p, int layer, char* smem_blk, char* smem) {
;     ...
; #pragma unroll
;       for (int mi = 0; mi < 2; ++mi)
; #pragma unroll
;         for (int ni = 0; ni < 2; ++ni)
; #pragma unroll
;           for (int reg = 0; reg < 16; ++reg) {
;             const int ii = 64 * wm + 32 * mi + (reg & 3) + 8 * (reg >> 2) + 4 * h, cc = 64 * wn + 32 * ni + r;
;             const size_t tok = (size_t)n * 128 + ii;
;             const unsigned uu = U[tok * 512 + g * 128 + cc];
;             const float uf = __uint_as_float(uu << 16);
;             Y[tok * DM + g * 128 + cc] = f2bf(uf * (acc[mi][ni][reg] + sb[ii]));
;           }
	v_add_f32_e32 v34, v34, v206
	v_lshlrev_b32_e32 v66, 16, v66
	v_add_f32_e32 v50, v50, v206
	v_lshlrev_b32_e32 v67, 16, v67
	v_add_f32_e32 v35, v35, v207
	v_lshlrev_b32_e32 v68, 16, v68
	v_add_f32_e32 v51, v51, v207
	v_lshlrev_b32_e32 v69, 16, v69
	v_add_f32_e32 v36, v36, v208
	v_lshlrev_b32_e32 v70, 16, v70
	v_add_f32_e32 v52, v52, v208
	v_lshlrev_b32_e32 v71, 16, v71
	v_add_f32_e32 v37, v37, v209
	v_lshlrev_b32_e32 v72, 16, v72
	v_add_f32_e32 v53, v53, v209
	v_lshlrev_b32_e32 v73, 16, v73
	v_add_f32_e32 v38, v38, v210
	v_lshlrev_b32_e32 v74, 16, v74
	v_add_f32_e32 v54, v54, v210
	v_lshlrev_b32_e32 v75, 16, v75
	v_add_f32_e32 v39, v39, v211
	v_lshlrev_b32_e32 v76, 16, v76
	v_add_f32_e32 v55, v55, v211
	v_lshlrev_b32_e32 v77, 16, v77
	v_add_f32_e32 v40, v40, v212
	v_lshlrev_b32_e32 v78, 16, v78
	v_add_f32_e32 v56, v56, v212
	v_lshlrev_b32_e32 v79, 16, v79
	v_add_f32_e32 v41, v41, v213
	v_lshlrev_b32_e32 v80, 16, v80
	v_add_f32_e32 v57, v57, v213
	v_lshlrev_b32_e32 v81, 16, v81
	v_mul_f32_e32 v34, v34, v66
	v_mul_f32_e32 v50, v50, v67
	v_mul_f32_e32 v35, v35, v68
	v_mul_f32_e32 v51, v51, v69
	v_mul_f32_e32 v36, v36, v70
	v_mul_f32_e32 v52, v52, v71
	v_mul_f32_e32 v37, v37, v72
	v_mul_f32_e32 v53, v53, v73
	v_mul_f32_e32 v38, v38, v74
	v_mul_f32_e32 v54, v54, v75
	v_mul_f32_e32 v39, v39, v76
	v_mul_f32_e32 v55, v55, v77
	v_mul_f32_e32 v40, v40, v78
	v_mul_f32_e32 v56, v56, v79
	v_mul_f32_e32 v41, v41, v80
	v_mul_f32_e32 v57, v57, v81
	v_cvt_pk_bf16_f32 v34, v34, v34
	v_cvt_pk_bf16_f32 v50, v50, v50
	v_cvt_pk_bf16_f32 v35, v35, v35
	v_cvt_pk_bf16_f32 v51, v51, v51
	v_cvt_pk_bf16_f32 v36, v36, v36
	v_cvt_pk_bf16_f32 v52, v52, v52
	v_cvt_pk_bf16_f32 v37, v37, v37
	v_cvt_pk_bf16_f32 v53, v53, v53
	v_cvt_pk_bf16_f32 v38, v38, v38
	v_cvt_pk_bf16_f32 v54, v54, v54
	v_cvt_pk_bf16_f32 v39, v39, v39
	v_cvt_pk_bf16_f32 v55, v55, v55
	v_cvt_pk_bf16_f32 v40, v40, v40
	v_cvt_pk_bf16_f32 v56, v56, v56
	v_cvt_pk_bf16_f32 v41, v41, v41
	v_cvt_pk_bf16_f32 v57, v57, v57
	global_load_dwordx4 v[222:225], v[126:127], off offset:128
	global_load_dwordx4 v[226:229], v[126:127], off offset:160
	s_add_u32 s58, s52, 0x8000
	s_addc_u32 s59, s53, 0
	global_load_ushort v98, v193, s[58:59]
	global_load_ushort v99, v193, s[58:59] offset:64
	global_load_ushort v100, v193, s[58:59] offset:1024
	global_load_ushort v101, v193, s[58:59] offset:1088
	global_load_ushort v102, v193, s[58:59] offset:2048
	global_load_ushort v103, v193, s[58:59] offset:2112
	global_load_ushort v104, v193, s[58:59] offset:3072
	global_load_ushort v105, v193, s[58:59] offset:3136
	s_add_u32 s58, s52, 0xa000
	s_addc_u32 s59, s53, 0
	global_load_ushort v106, v193, s[58:59]
	global_load_ushort v107, v193, s[58:59] offset:64
	global_load_ushort v108, v193, s[58:59] offset:1024
	global_load_ushort v109, v193, s[58:59] offset:1088
	global_load_ushort v110, v193, s[58:59] offset:2048
	global_load_ushort v111, v193, s[58:59] offset:2112
	global_load_ushort v112, v193, s[58:59] offset:3072
	global_load_ushort v113, v193, s[58:59] offset:3136
	s_add_u32 s60, s56, 0x0
	s_addc_u32 s61, s57, 0
	global_store_short v194, v34, s[60:61]
	global_store_short v194, v50, s[60:61] offset:64
	global_store_short v195, v35, s[60:61]
	global_store_short v195, v51, s[60:61] offset:64
	global_store_short v196, v36, s[60:61]
	global_store_short v196, v52, s[60:61] offset:64
	global_store_short v197, v37, s[60:61]
	global_store_short v197, v53, s[60:61] offset:64
	s_add_u32 s60, s56, 0x8000
	s_addc_u32 s61, s57, 0
	global_store_short v194, v38, s[60:61]
	global_store_short v194, v54, s[60:61] offset:64
	global_store_short v195, v39, s[60:61]
	global_store_short v195, v55, s[60:61] offset:64
	global_store_short v196, v40, s[60:61]
	global_store_short v196, v56, s[60:61] offset:64
	global_store_short v197, v41, s[60:61]
	global_store_short v197, v57, s[60:61] offset:64
	s_waitcnt vmcnt(34)
	v_add_f32_e32 v42, v42, v214
	v_lshlrev_b32_e32 v82, 16, v82
	v_add_f32_e32 v58, v58, v214
	v_lshlrev_b32_e32 v83, 16, v83
	v_add_f32_e32 v43, v43, v215
	v_lshlrev_b32_e32 v84, 16, v84
	v_add_f32_e32 v59, v59, v215
	v_lshlrev_b32_e32 v85, 16, v85
	v_add_f32_e32 v44, v44, v216
	v_lshlrev_b32_e32 v86, 16, v86
	v_add_f32_e32 v60, v60, v216
	v_lshlrev_b32_e32 v87, 16, v87
	v_add_f32_e32 v45, v45, v217
	v_lshlrev_b32_e32 v88, 16, v88
	v_add_f32_e32 v61, v61, v217
	v_lshlrev_b32_e32 v89, 16, v89
	v_add_f32_e32 v46, v46, v218
	v_lshlrev_b32_e32 v90, 16, v90
	v_add_f32_e32 v62, v62, v218
	v_lshlrev_b32_e32 v91, 16, v91
	v_add_f32_e32 v47, v47, v219
	v_lshlrev_b32_e32 v92, 16, v92
	v_add_f32_e32 v63, v63, v219
	v_lshlrev_b32_e32 v93, 16, v93
	v_add_f32_e32 v48, v48, v220
	v_lshlrev_b32_e32 v94, 16, v94
	v_add_f32_e32 v64, v64, v220
	v_lshlrev_b32_e32 v95, 16, v95
	v_add_f32_e32 v49, v49, v221
	v_lshlrev_b32_e32 v96, 16, v96
	v_add_f32_e32 v65, v65, v221
	v_lshlrev_b32_e32 v97, 16, v97
	v_mul_f32_e32 v42, v42, v82
	v_mul_f32_e32 v58, v58, v83
	v_mul_f32_e32 v43, v43, v84
	v_mul_f32_e32 v59, v59, v85
	v_mul_f32_e32 v44, v44, v86
	v_mul_f32_e32 v60, v60, v87
	v_mul_f32_e32 v45, v45, v88
	v_mul_f32_e32 v61, v61, v89
	v_mul_f32_e32 v46, v46, v90
	v_mul_f32_e32 v62, v62, v91
	v_mul_f32_e32 v47, v47, v92
	v_mul_f32_e32 v63, v63, v93
	v_mul_f32_e32 v48, v48, v94
	v_mul_f32_e32 v64, v64, v95
	v_mul_f32_e32 v49, v49, v96
	v_mul_f32_e32 v65, v65, v97
	v_cvt_pk_bf16_f32 v42, v42, v42
	v_cvt_pk_bf16_f32 v58, v58, v58
	v_cvt_pk_bf16_f32 v43, v43, v43
	v_cvt_pk_bf16_f32 v59, v59, v59
	v_cvt_pk_bf16_f32 v44, v44, v44
	v_cvt_pk_bf16_f32 v60, v60, v60
	v_cvt_pk_bf16_f32 v45, v45, v45
	v_cvt_pk_bf16_f32 v61, v61, v61
	v_cvt_pk_bf16_f32 v46, v46, v46
	v_cvt_pk_bf16_f32 v62, v62, v62
; DI void mix_phase(const Params& p, int layer, char* smem_blk, char* smem) {
;     ...
; #pragma unroll
;       for (int mi = 0; mi < 2; ++mi)
; #pragma unroll
;         for (int ni = 0; ni < 2; ++ni)
; #pragma unroll
;           for (int reg = 0; reg < 16; ++reg) {
;             const int ii = 64 * wm + 32 * mi + (reg & 3) + 8 * (reg >> 2) + 4 * h, cc = 64 * wn + 32 * ni + r;
;             const size_t tok = (size_t)n * 128 + ii;
;             const unsigned uu = U[tok * 512 + g * 128 + cc];
;             const float uf = __uint_as_float(uu << 16);
;             Y[tok * DM + g * 128 + cc] = f2bf(uf * (acc[mi][ni][reg] + sb[ii]));
;           }
	v_cvt_pk_bf16_f32 v47, v47, v47
	v_cvt_pk_bf16_f32 v63, v63, v63
	v_cvt_pk_bf16_f32 v48, v48, v48
	v_cvt_pk_bf16_f32 v64, v64, v64
	v_cvt_pk_bf16_f32 v49, v49, v49
	v_cvt_pk_bf16_f32 v65, v65, v65
	global_load_dwordx4 v[206:209], v[126:127], off offset:192
	global_load_dwordx4 v[210:213], v[126:127], off offset:224
	s_add_u32 s58, s52, 0xc000
	s_addc_u32 s59, s53, 0
	global_load_ushort v66, v193, s[58:59]
	global_load_ushort v67, v193, s[58:59] offset:64
	global_load_ushort v68, v193, s[58:59] offset:1024
	global_load_ushort v69, v193, s[58:59] offset:1088
	global_load_ushort v70, v193, s[58:59] offset:2048
	global_load_ushort v71, v193, s[58:59] offset:2112
	global_load_ushort v72, v193, s[58:59] offset:3072
	global_load_ushort v73, v193, s[58:59] offset:3136
	s_add_u32 s58, s52, 0xe000
	s_addc_u32 s59, s53, 0
	global_load_ushort v74, v193, s[58:59]
	global_load_ushort v75, v193, s[58:59] offset:64
	global_load_ushort v76, v193, s[58:59] offset:1024
	global_load_ushort v77, v193, s[58:59] offset:1088
	global_load_ushort v78, v193, s[58:59] offset:2048
	global_load_ushort v79, v193, s[58:59] offset:2112
	global_load_ushort v80, v193, s[58:59] offset:3072
	global_load_ushort v81, v193, s[58:59] offset:3136
	s_add_u32 s60, s56, 0x10000
	s_addc_u32 s61, s57, 0
	global_store_short v194, v42, s[60:61]
	global_store_short v194, v58, s[60:61] offset:64
	global_store_short v195, v43, s[60:61]
	global_store_short v195, v59, s[60:61] offset:64
	global_store_short v196, v44, s[60:61]
	global_store_short v196, v60, s[60:61] offset:64
	global_store_short v197, v45, s[60:61]
	global_store_short v197, v61, s[60:61] offset:64
	s_add_u32 s60, s56, 0x18000
	s_addc_u32 s61, s57, 0
	global_store_short v194, v46, s[60:61]
	global_store_short v194, v62, s[60:61] offset:64
	global_store_short v195, v47, s[60:61]
	global_store_short v195, v63, s[60:61] offset:64
	global_store_short v196, v48, s[60:61]
	global_store_short v196, v64, s[60:61] offset:64
	global_store_short v197, v49, s[60:61]
	global_store_short v197, v65, s[60:61] offset:64
	s_waitcnt vmcnt(50)
	v_add_f32_e32 v18, v18, v222
	v_lshlrev_b32_e32 v98, 16, v98
	v_add_f32_e32 v2, v2, v222
	v_lshlrev_b32_e32 v99, 16, v99
	v_add_f32_e32 v19, v19, v223
	v_lshlrev_b32_e32 v100, 16, v100
	v_add_f32_e32 v3, v3, v223
	v_lshlrev_b32_e32 v101, 16, v101
	v_add_f32_e32 v20, v20, v224
	v_lshlrev_b32_e32 v102, 16, v102
	v_add_f32_e32 v4, v4, v224
	v_lshlrev_b32_e32 v103, 16, v103
	v_add_f32_e32 v21, v21, v225
	v_lshlrev_b32_e32 v104, 16, v104
	v_add_f32_e32 v5, v5, v225
	v_lshlrev_b32_e32 v105, 16, v105
	v_add_f32_e32 v22, v22, v226
	v_lshlrev_b32_e32 v106, 16, v106
	v_add_f32_e32 v6, v6, v226
	v_lshlrev_b32_e32 v107, 16, v107
	v_add_f32_e32 v23, v23, v227
	v_lshlrev_b32_e32 v108, 16, v108
	v_add_f32_e32 v7, v7, v227
	v_lshlrev_b32_e32 v109, 16, v109
	v_add_f32_e32 v24, v24, v228
	v_lshlrev_b32_e32 v110, 16, v110
	v_add_f32_e32 v8, v8, v228
	v_lshlrev_b32_e32 v111, 16, v111
	v_add_f32_e32 v25, v25, v229
	v_lshlrev_b32_e32 v112, 16, v112
	v_add_f32_e32 v9, v9, v229
	v_lshlrev_b32_e32 v113, 16, v113
	v_mul_f32_e32 v18, v18, v98
	v_mul_f32_e32 v2, v2, v99
	v_mul_f32_e32 v19, v19, v100
	v_mul_f32_e32 v3, v3, v101
	v_mul_f32_e32 v20, v20, v102
	v_mul_f32_e32 v4, v4, v103
	v_mul_f32_e32 v21, v21, v104
	v_mul_f32_e32 v5, v5, v105
	v_mul_f32_e32 v22, v22, v106
	v_mul_f32_e32 v6, v6, v107
	v_mul_f32_e32 v23, v23, v108
	v_mul_f32_e32 v7, v7, v109
	v_mul_f32_e32 v24, v24, v110
	v_mul_f32_e32 v8, v8, v111
	v_mul_f32_e32 v25, v25, v112
	v_mul_f32_e32 v9, v9, v113
	v_cvt_pk_bf16_f32 v18, v18, v18
	v_cvt_pk_bf16_f32 v2, v2, v2
	v_cvt_pk_bf16_f32 v19, v19, v19
	v_cvt_pk_bf16_f32 v3, v3, v3
	v_cvt_pk_bf16_f32 v20, v20, v20
	v_cvt_pk_bf16_f32 v4, v4, v4
	v_cvt_pk_bf16_f32 v21, v21, v21
	v_cvt_pk_bf16_f32 v5, v5, v5
	v_cvt_pk_bf16_f32 v22, v22, v22
	v_cvt_pk_bf16_f32 v6, v6, v6
	v_cvt_pk_bf16_f32 v23, v23, v23
	v_cvt_pk_bf16_f32 v7, v7, v7
	v_cvt_pk_bf16_f32 v24, v24, v24
	v_cvt_pk_bf16_f32 v8, v8, v8
	v_cvt_pk_bf16_f32 v25, v25, v25
	v_cvt_pk_bf16_f32 v9, v9, v9
	s_add_u32 s60, s56, 0x20000
	s_addc_u32 s61, s57, 0
	global_store_short v194, v18, s[60:61]
	global_store_short v194, v2, s[60:61] offset:64
	global_store_short v195, v19, s[60:61]
	global_store_short v195, v3, s[60:61] offset:64
	global_store_short v196, v20, s[60:61]
	global_store_short v196, v4, s[60:61] offset:64
	global_store_short v197, v21, s[60:61]
	global_store_short v197, v5, s[60:61] offset:64
	s_add_u32 s60, s56, 0x28000
	s_addc_u32 s61, s57, 0
	global_store_short v194, v22, s[60:61]
	global_store_short v194, v6, s[60:61] offset:64
	global_store_short v195, v23, s[60:61]
	global_store_short v195, v7, s[60:61] offset:64
	global_store_short v196, v24, s[60:61]
	global_store_short v196, v8, s[60:61] offset:64
	global_store_short v197, v25, s[60:61]
	global_store_short v197, v9, s[60:61] offset:64
	s_waitcnt vmcnt(32)
; DI void mix_phase(const Params& p, int layer, char* smem_blk, char* smem) {
;     ...
; #pragma unroll
;       for (int mi = 0; mi < 2; ++mi)
; #pragma unroll
;         for (int ni = 0; ni < 2; ++ni)
; #pragma unroll
;           for (int reg = 0; reg < 16; ++reg) {
;             const int ii = 64 * wm + 32 * mi + (reg & 3) + 8 * (reg >> 2) + 4 * h, cc = 64 * wn + 32 * ni + r;
;             const size_t tok = (size_t)n * 128 + ii;
;             const unsigned uu = U[tok * 512 + g * 128 + cc];
;             const float uf = __uint_as_float(uu << 16);
;             Y[tok * DM + g * 128 + cc] = f2bf(uf * (acc[mi][ni][reg] + sb[ii]));
;           }
	v_add_f32_e32 v26, v26, v206
	v_lshlrev_b32_e32 v66, 16, v66
	v_add_f32_e32 v10, v10, v206
	v_lshlrev_b32_e32 v67, 16, v67
	v_add_f32_e32 v27, v27, v207
	v_lshlrev_b32_e32 v68, 16, v68
	v_add_f32_e32 v11, v11, v207
	v_lshlrev_b32_e32 v69, 16, v69
	v_add_f32_e32 v28, v28, v208
	v_lshlrev_b32_e32 v70, 16, v70
	v_add_f32_e32 v12, v12, v208
	v_lshlrev_b32_e32 v71, 16, v71
	v_add_f32_e32 v29, v29, v209
	v_lshlrev_b32_e32 v72, 16, v72
	v_add_f32_e32 v13, v13, v209
	v_lshlrev_b32_e32 v73, 16, v73
	v_add_f32_e32 v30, v30, v210
	v_lshlrev_b32_e32 v74, 16, v74
	v_add_f32_e32 v14, v14, v210
	v_lshlrev_b32_e32 v75, 16, v75
	v_add_f32_e32 v31, v31, v211
	v_lshlrev_b32_e32 v76, 16, v76
	v_add_f32_e32 v15, v15, v211
	v_lshlrev_b32_e32 v77, 16, v77
	v_add_f32_e32 v32, v32, v212
	v_lshlrev_b32_e32 v78, 16, v78
	v_add_f32_e32 v16, v16, v212
	v_lshlrev_b32_e32 v79, 16, v79
	v_add_f32_e32 v33, v33, v213
	v_lshlrev_b32_e32 v80, 16, v80
	v_add_f32_e32 v17, v17, v213
	v_lshlrev_b32_e32 v81, 16, v81
	v_mul_f32_e32 v26, v26, v66
	v_mul_f32_e32 v10, v10, v67
	v_mul_f32_e32 v27, v27, v68
	v_mul_f32_e32 v11, v11, v69
	v_mul_f32_e32 v28, v28, v70
	v_mul_f32_e32 v12, v12, v71
	v_mul_f32_e32 v29, v29, v72
	v_mul_f32_e32 v13, v13, v73
	v_mul_f32_e32 v30, v30, v74
	v_mul_f32_e32 v14, v14, v75
	v_mul_f32_e32 v31, v31, v76
	v_mul_f32_e32 v15, v15, v77
	v_mul_f32_e32 v32, v32, v78
	v_mul_f32_e32 v16, v16, v79
	v_mul_f32_e32 v33, v33, v80
	v_mul_f32_e32 v17, v17, v81
	v_cvt_pk_bf16_f32 v26, v26, v26
	v_cvt_pk_bf16_f32 v10, v10, v10
	v_cvt_pk_bf16_f32 v27, v27, v27
	v_cvt_pk_bf16_f32 v11, v11, v11
	v_cvt_pk_bf16_f32 v28, v28, v28
	v_cvt_pk_bf16_f32 v12, v12, v12
	v_cvt_pk_bf16_f32 v29, v29, v29
	v_cvt_pk_bf16_f32 v13, v13, v13
	v_cvt_pk_bf16_f32 v30, v30, v30
	v_cvt_pk_bf16_f32 v14, v14, v14
	v_cvt_pk_bf16_f32 v31, v31, v31
	v_cvt_pk_bf16_f32 v15, v15, v15
	v_cvt_pk_bf16_f32 v32, v32, v32
	v_cvt_pk_bf16_f32 v16, v16, v16
	v_cvt_pk_bf16_f32 v33, v33, v33
	v_cvt_pk_bf16_f32 v17, v17, v17
	s_add_u32 s60, s56, 0x30000
	s_addc_u32 s61, s57, 0
	global_store_short v194, v26, s[60:61]
	global_store_short v194, v10, s[60:61] offset:64
	global_store_short v195, v27, s[60:61]
	global_store_short v195, v11, s[60:61] offset:64
	global_store_short v196, v28, s[60:61]
	global_store_short v196, v12, s[60:61] offset:64
	global_store_short v197, v29, s[60:61]
	global_store_short v197, v13, s[60:61] offset:64
	s_add_u32 s60, s56, 0x38000
	s_addc_u32 s61, s57, 0
	global_store_short v194, v30, s[60:61]
	global_store_short v194, v14, s[60:61] offset:64
	global_store_short v195, v31, s[60:61]
	global_store_short v195, v15, s[60:61] offset:64
	global_store_short v196, v32, s[60:61]
	global_store_short v196, v16, s[60:61] offset:64
	global_store_short v197, v33, s[60:61]
	global_store_short v197, v17, s[60:61] offset:64
	s_branch .LBB0_430

; #define MFMA32(a, b, c) __builtin_amdgcn_mfma_f32_32x32x16_bf16((a), (b), (c), 0, 0, 0)
; DI void gemm256(const char* a_u, unsigned a_voff, size_t astep, const char* b_u, unsigned b_voff, size_t bstep, int nk, char* smem, f32x16 (&acc)[4][2]) {
;     ...
;   for (int kt = 0; kt < nk; ++kt) {
;     const int cur = kt & 1, k2 = (kt + 2 < last) ? kt + 2 : last;
;     const char* S = smem + cur * 2 * T2;
;     char* D = smem + (cur ^ 1) * 2 * T2;
;     const char* an = a_u + (size_t)k2 * 128;
;     const char* bn = b_u + (size_t)k2 * 128;
; #pragma unroll
;     for (int s = 0; s < 4; ++s) {
;       bf16x8 a[4], b[2];
; #pragma unroll
;       for (int mi = 0; mi < 4; ++mi) a[mi] = *(const bf16x8*)(S + aoff + mi * 32 * LROW + s * 32);
; #pragma unroll
;       for (int ni = 0; ni < 2; ++ni) b[ni] = *(const bf16x8*)(S + boff + ni * 32 * LROW + s * 32);
;       *(u32x4*)(D + soff + s * 64 * LROW) = ra[s];
;       *(u32x4*)(D + T2 + soff + s * 64 * LROW) = rb[s];
;       ra[s] = *(const u32x4*)(an + s * astep + a_voff);
;       rb[s] = *(const u32x4*)(bn + s * bstep + b_voff);
; #pragma unroll
;       for (int mi = 0; mi < 4; ++mi)
; #pragma unroll
;         for (int ni = 0; ni < 2; ++ni) acc[mi][ni] = MFMA32(a[mi], b[ni], acc[mi][ni]);
;     }
;     __syncthreads();
;   }
.Lg_outproj_loop:
	s_add_i32 s56, s56, 1
	s_add_u32 m0, s59, 0x8000
	s_nop 0
	global_load_lds_dwordx4 v164, s[54:55]
	global_load_lds_dwordx4 v165, s[54:55] offset:1024
	global_load_lds_dwordx4 v130, s[54:55] offset:2048
	global_load_lds_dwordx4 v131, s[54:55] offset:3072
	s_waitcnt lgkmcnt(0)
	v_mfma_f32_16x16x32_bf16 v[114:117], v[196:199], v[212:215], v[114:117]
	ds_read_b128 v[220:223], v194 offset:2048
	v_mfma_f32_16x16x32_bf16 v[118:121], v[196:199], v[216:219], v[118:121]
	ds_read_b128 v[224:227], v194 offset:6144
	v_mfma_f32_16x16x32_bf16 v[98:101], v[196:199], v[242:245], v[98:101]
	ds_read_b128 v[228:231], v194 offset:10240
	v_mfma_f32_16x16x32_bf16 v[102:105], v[196:199], v[246:249], v[102:105]
	ds_read_b128 v[238:241], v194 offset:14336
	v_mfma_f32_16x16x32_bf16 v[82:85], v[200:203], v[212:215], v[82:85]
	v_mfma_f32_16x16x32_bf16 v[86:89], v[200:203], v[216:219], v[86:89]
	v_mfma_f32_16x16x32_bf16 v[66:69], v[200:203], v[242:245], v[66:69]
	v_mfma_f32_16x16x32_bf16 v[70:73], v[200:203], v[246:249], v[70:73]
	v_mfma_f32_16x16x32_bf16 v[50:53], v[204:207], v[212:215], v[50:53]
	v_mfma_f32_16x16x32_bf16 v[54:57], v[204:207], v[216:219], v[54:57]
	v_mfma_f32_16x16x32_bf16 v[34:37], v[204:207], v[242:245], v[34:37]
	v_mfma_f32_16x16x32_bf16 v[38:41], v[204:207], v[246:249], v[38:41]
	v_mfma_f32_16x16x32_bf16 v[18:21], v[208:211], v[212:215], v[18:21]
	v_mfma_f32_16x16x32_bf16 v[22:25], v[208:211], v[216:219], v[22:25]
	v_mfma_f32_16x16x32_bf16 v[2:5], v[208:211], v[242:245], v[2:5]
	v_mfma_f32_16x16x32_bf16 v[6:9], v[208:211], v[246:249], v[6:9]
	s_add_u32 m0, s58, 0x8000
	s_nop 0
	global_load_lds_dwordx4 v164, s[52:53]
	global_load_lds_dwordx4 v165, s[52:53] offset:1024
	global_load_lds_dwordx4 v130, s[52:53] offset:2048
	global_load_lds_dwordx4 v131, s[52:53] offset:3072
	s_waitcnt lgkmcnt(0)
	v_mfma_f32_16x16x32_bf16 v[122:125], v[220:223], v[212:215], v[122:125]
	ds_read_b128 v[196:199], v195 offset:0
	v_mfma_f32_16x16x32_bf16 v[126:129], v[220:223], v[216:219], v[126:129]
	ds_read_b128 v[140:143], v161 offset:0
	v_mfma_f32_16x16x32_bf16 v[106:109], v[220:223], v[242:245], v[106:109]
	ds_read_b128 v[144:147], v161 offset:2048
	v_mfma_f32_16x16x32_bf16 v[110:113], v[220:223], v[246:249], v[110:113]
	ds_read_b128 v[148:151], v161 offset:4096
	v_mfma_f32_16x16x32_bf16 v[90:93], v[224:227], v[212:215], v[90:93]
	ds_read_b128 v[152:155], v161 offset:6144
	v_mfma_f32_16x16x32_bf16 v[94:97], v[224:227], v[216:219], v[94:97]
	ds_read_b128 v[200:203], v195 offset:4096
	v_mfma_f32_16x16x32_bf16 v[74:77], v[224:227], v[242:245], v[74:77]
	ds_read_b128 v[204:207], v195 offset:8192
	v_mfma_f32_16x16x32_bf16 v[78:81], v[224:227], v[246:249], v[78:81]
	ds_read_b128 v[208:211], v195 offset:12288
	v_mfma_f32_16x16x32_bf16 v[58:61], v[228:231], v[212:215], v[58:61]
	v_mfma_f32_16x16x32_bf16 v[62:65], v[228:231], v[216:219], v[62:65]
	v_mfma_f32_16x16x32_bf16 v[42:45], v[228:231], v[242:245], v[42:45]
	v_mfma_f32_16x16x32_bf16 v[46:49], v[228:231], v[246:249], v[46:49]
	v_mfma_f32_16x16x32_bf16 v[26:29], v[238:241], v[212:215], v[26:29]
	v_mfma_f32_16x16x32_bf16 v[30:33], v[238:241], v[216:219], v[30:33]
	v_mfma_f32_16x16x32_bf16 v[10:13], v[238:241], v[242:245], v[10:13]
	v_mfma_f32_16x16x32_bf16 v[14:17], v[238:241], v[246:249], v[14:17]
	s_waitcnt lgkmcnt(0)
	v_mfma_f32_16x16x32_bf16 v[114:117], v[196:199], v[140:143], v[114:117]
	ds_read_b128 v[220:223], v195 offset:2048
	v_mfma_f32_16x16x32_bf16 v[118:121], v[196:199], v[144:147], v[118:121]
	ds_read_b128 v[224:227], v195 offset:6144
	v_mfma_f32_16x16x32_bf16 v[98:101], v[196:199], v[148:151], v[98:101]
	ds_read_b128 v[228:231], v195 offset:10240
	v_mfma_f32_16x16x32_bf16 v[102:105], v[196:199], v[152:155], v[102:105]
	ds_read_b128 v[238:241], v195 offset:14336
	v_mfma_f32_16x16x32_bf16 v[82:85], v[200:203], v[140:143], v[82:85]
	v_mfma_f32_16x16x32_bf16 v[86:89], v[200:203], v[144:147], v[86:89]
	v_mfma_f32_16x16x32_bf16 v[66:69], v[200:203], v[148:151], v[66:69]
	v_mfma_f32_16x16x32_bf16 v[70:73], v[200:203], v[152:155], v[70:73]
	v_mfma_f32_16x16x32_bf16 v[50:53], v[204:207], v[140:143], v[50:53]
	v_mfma_f32_16x16x32_bf16 v[54:57], v[204:207], v[144:147], v[54:57]
	v_mfma_f32_16x16x32_bf16 v[34:37], v[204:207], v[148:151], v[34:37]
	v_mfma_f32_16x16x32_bf16 v[38:41], v[204:207], v[152:155], v[38:41]
	v_mfma_f32_16x16x32_bf16 v[18:21], v[208:211], v[140:143], v[18:21]
	v_mfma_f32_16x16x32_bf16 v[22:25], v[208:211], v[144:147], v[22:25]
	v_mfma_f32_16x16x32_bf16 v[2:5], v[208:211], v[148:151], v[2:5]
	v_mfma_f32_16x16x32_bf16 v[6:9], v[208:211], v[152:155], v[6:9]
	s_waitcnt lgkmcnt(0)
	v_mfma_f32_16x16x32_bf16 v[122:125], v[220:223], v[140:143], v[122:125]
	v_mfma_f32_16x16x32_bf16 v[126:129], v[220:223], v[144:147], v[126:129]
	v_mfma_f32_16x16x32_bf16 v[106:109], v[220:223], v[148:151], v[106:109]
	v_mfma_f32_16x16x32_bf16 v[110:113], v[220:223], v[152:155], v[110:113]
	v_mfma_f32_16x16x32_bf16 v[90:93], v[224:227], v[140:143], v[90:93]
	v_mfma_f32_16x16x32_bf16 v[94:97], v[224:227], v[144:147], v[94:97]
	v_mfma_f32_16x16x32_bf16 v[74:77], v[224:227], v[148:151], v[74:77]
	v_mfma_f32_16x16x32_bf16 v[78:81], v[224:227], v[152:155], v[78:81]
	v_mfma_f32_16x16x32_bf16 v[58:61], v[228:231], v[140:143], v[58:61]
	v_mfma_f32_16x16x32_bf16 v[62:65], v[228:231], v[144:147], v[62:65]
	v_mfma_f32_16x16x32_bf16 v[42:45], v[228:231], v[148:151], v[42:45]
	v_mfma_f32_16x16x32_bf16 v[46:49], v[228:231], v[152:155], v[46:49]
	v_mfma_f32_16x16x32_bf16 v[26:29], v[238:241], v[140:143], v[26:29]
	v_mfma_f32_16x16x32_bf16 v[30:33], v[238:241], v[144:147], v[30:33]
	v_mfma_f32_16x16x32_bf16 v[10:13], v[238:241], v[148:151], v[10:13]
	v_mfma_f32_16x16x32_bf16 v[14:17], v[238:241], v[152:155], v[14:17]
	s_cmp_lt_u32 s56, s57
	s_cselect_b32 s60, 0x80, 0
	s_add_u32 s52, s52, s60
	s_addc_u32 s53, s53, 0
	s_add_u32 s54, s54, s60
	s_addc_u32 s55, s55, 0
	s_waitcnt vmcnt(0)
	s_barrier
; #define MFMA32(a, b, c) __builtin_amdgcn_mfma_f32_32x32x16_bf16((a), (b), (c), 0, 0, 0)
; DI void gemm256(const char* a_u, unsigned a_voff, size_t astep, const char* b_u, unsigned b_voff, size_t bstep, int nk, char* smem, f32x16 (&acc)[4][2]) {
;     ...
;   for (int kt = 0; kt < nk; ++kt) {
;     const int cur = kt & 1, k2 = (kt + 2 < last) ? kt + 2 : last;
;     const char* S = smem + cur * 2 * T2;
;     char* D = smem + (cur ^ 1) * 2 * T2;
;     const char* an = a_u + (size_t)k2 * 128;
;     const char* bn = b_u + (size_t)k2 * 128;
; #pragma unroll
;     for (int s = 0; s < 4; ++s) {
;       bf16x8 a[4], b[2];
; #pragma unroll
;       for (int mi = 0; mi < 4; ++mi) a[mi] = *(const bf16x8*)(S + aoff + mi * 32 * LROW + s * 32);
; #pragma unroll
;       for (int ni = 0; ni < 2; ++ni) b[ni] = *(const bf16x8*)(S + boff + ni * 32 * LROW + s * 32);
;       *(u32x4*)(D + soff + s * 64 * LROW) = ra[s];
;       *(u32x4*)(D + T2 + soff + s * 64 * LROW) = rb[s];
;       ra[s] = *(const u32x4*)(an + s * astep + a_voff);
;       rb[s] = *(const u32x4*)(bn + s * bstep + b_voff);
; #pragma unroll
;       for (int mi = 0; mi < 4; ++mi)
; #pragma unroll
;         for (int ni = 0; ni < 2; ++ni) acc[mi][ni] = MFMA32(a[mi], b[ni], acc[mi][ni]);
;     }
;     __syncthreads();
;   }
	ds_read_b128 v[196:199], v194 offset:32768
	ds_read_b128 v[212:215], v160 offset:32768
	ds_read_b128 v[216:219], v160 offset:34816
	ds_read_b128 v[242:245], v160 offset:36864
	ds_read_b128 v[246:249], v160 offset:38912
	ds_read_b128 v[200:203], v194 offset:36864
	ds_read_b128 v[204:207], v194 offset:40960
	ds_read_b128 v[208:211], v194 offset:45056
	s_add_i32 s56, s56, 1
	s_add_u32 m0, s59, 0x0
	s_nop 0
	global_load_lds_dwordx4 v164, s[54:55]
	global_load_lds_dwordx4 v165, s[54:55] offset:1024
	global_load_lds_dwordx4 v130, s[54:55] offset:2048
	global_load_lds_dwordx4 v131, s[54:55] offset:3072
	s_waitcnt lgkmcnt(0)
	v_mfma_f32_16x16x32_bf16 v[114:117], v[196:199], v[212:215], v[114:117]
	ds_read_b128 v[220:223], v194 offset:34816
	v_mfma_f32_16x16x32_bf16 v[118:121], v[196:199], v[216:219], v[118:121]
	ds_read_b128 v[224:227], v194 offset:38912
	v_mfma_f32_16x16x32_bf16 v[98:101], v[196:199], v[242:245], v[98:101]
	ds_read_b128 v[228:231], v194 offset:43008
	v_mfma_f32_16x16x32_bf16 v[102:105], v[196:199], v[246:249], v[102:105]
	ds_read_b128 v[238:241], v194 offset:47104
	v_mfma_f32_16x16x32_bf16 v[82:85], v[200:203], v[212:215], v[82:85]
	v_mfma_f32_16x16x32_bf16 v[86:89], v[200:203], v[216:219], v[86:89]
	v_mfma_f32_16x16x32_bf16 v[66:69], v[200:203], v[242:245], v[66:69]
	v_mfma_f32_16x16x32_bf16 v[70:73], v[200:203], v[246:249], v[70:73]
	v_mfma_f32_16x16x32_bf16 v[50:53], v[204:207], v[212:215], v[50:53]
	v_mfma_f32_16x16x32_bf16 v[54:57], v[204:207], v[216:219], v[54:57]
	v_mfma_f32_16x16x32_bf16 v[34:37], v[204:207], v[242:245], v[34:37]
	v_mfma_f32_16x16x32_bf16 v[38:41], v[204:207], v[246:249], v[38:41]
	v_mfma_f32_16x16x32_bf16 v[18:21], v[208:211], v[212:215], v[18:21]
	v_mfma_f32_16x16x32_bf16 v[22:25], v[208:211], v[216:219], v[22:25]
	v_mfma_f32_16x16x32_bf16 v[2:5], v[208:211], v[242:245], v[2:5]
	v_mfma_f32_16x16x32_bf16 v[6:9], v[208:211], v[246:249], v[6:9]
	s_add_u32 m0, s58, 0x0
	s_nop 0
	global_load_lds_dwordx4 v164, s[52:53]
	global_load_lds_dwordx4 v165, s[52:53] offset:1024
	global_load_lds_dwordx4 v130, s[52:53] offset:2048
	global_load_lds_dwordx4 v131, s[52:53] offset:3072
	s_waitcnt lgkmcnt(0)
	v_mfma_f32_16x16x32_bf16 v[122:125], v[220:223], v[212:215], v[122:125]
	ds_read_b128 v[196:199], v195 offset:32768
	v_mfma_f32_16x16x32_bf16 v[126:129], v[220:223], v[216:219], v[126:129]
	ds_read_b128 v[140:143], v161 offset:32768
	v_mfma_f32_16x16x32_bf16 v[106:109], v[220:223], v[242:245], v[106:109]
	ds_read_b128 v[144:147], v161 offset:34816
	v_mfma_f32_16x16x32_bf16 v[110:113], v[220:223], v[246:249], v[110:113]
	ds_read_b128 v[148:151], v161 offset:36864
	v_mfma_f32_16x16x32_bf16 v[90:93], v[224:227], v[212:215], v[90:93]
	ds_read_b128 v[152:155], v161 offset:38912
	v_mfma_f32_16x16x32_bf16 v[94:97], v[224:227], v[216:219], v[94:97]
	ds_read_b128 v[200:203], v195 offset:36864
	v_mfma_f32_16x16x32_bf16 v[74:77], v[224:227], v[242:245], v[74:77]
	ds_read_b128 v[204:207], v195 offset:40960
	v_mfma_f32_16x16x32_bf16 v[78:81], v[224:227], v[246:249], v[78:81]
	ds_read_b128 v[208:211], v195 offset:45056
	v_mfma_f32_16x16x32_bf16 v[58:61], v[228:231], v[212:215], v[58:61]
	v_mfma_f32_16x16x32_bf16 v[62:65], v[228:231], v[216:219], v[62:65]
	v_mfma_f32_16x16x32_bf16 v[42:45], v[228:231], v[242:245], v[42:45]
	v_mfma_f32_16x16x32_bf16 v[46:49], v[228:231], v[246:249], v[46:49]
	v_mfma_f32_16x16x32_bf16 v[26:29], v[238:241], v[212:215], v[26:29]
	v_mfma_f32_16x16x32_bf16 v[30:33], v[238:241], v[216:219], v[30:33]
	v_mfma_f32_16x16x32_bf16 v[10:13], v[238:241], v[242:245], v[10:13]
	v_mfma_f32_16x16x32_bf16 v[14:17], v[238:241], v[246:249], v[14:17]
	s_waitcnt lgkmcnt(0)
	v_mfma_f32_16x16x32_bf16 v[114:117], v[196:199], v[140:143], v[114:117]
	ds_read_b128 v[220:223], v195 offset:34816
	v_mfma_f32_16x16x32_bf16 v[118:121], v[196:199], v[144:147], v[118:121]
	ds_read_b128 v[224:227], v195 offset:38912
	v_mfma_f32_16x16x32_bf16 v[98:101], v[196:199], v[148:151], v[98:101]
	ds_read_b128 v[228:231], v195 offset:43008
	v_mfma_f32_16x16x32_bf16 v[102:105], v[196:199], v[152:155], v[102:105]
	ds_read_b128 v[238:241], v195 offset:47104
	v_mfma_f32_16x16x32_bf16 v[82:85], v[200:203], v[140:143], v[82:85]
	v_mfma_f32_16x16x32_bf16 v[86:89], v[200:203], v[144:147], v[86:89]
	v_mfma_f32_16x16x32_bf16 v[66:69], v[200:203], v[148:151], v[66:69]
	v_mfma_f32_16x16x32_bf16 v[70:73], v[200:203], v[152:155], v[70:73]
	v_mfma_f32_16x16x32_bf16 v[50:53], v[204:207], v[140:143], v[50:53]
	v_mfma_f32_16x16x32_bf16 v[54:57], v[204:207], v[144:147], v[54:57]
	v_mfma_f32_16x16x32_bf16 v[34:37], v[204:207], v[148:151], v[34:37]
	v_mfma_f32_16x16x32_bf16 v[38:41], v[204:207], v[152:155], v[38:41]
	v_mfma_f32_16x16x32_bf16 v[18:21], v[208:211], v[140:143], v[18:21]
	v_mfma_f32_16x16x32_bf16 v[22:25], v[208:211], v[144:147], v[22:25]
	v_mfma_f32_16x16x32_bf16 v[2:5], v[208:211], v[148:151], v[2:5]
	v_mfma_f32_16x16x32_bf16 v[6:9], v[208:211], v[152:155], v[6:9]
	s_waitcnt lgkmcnt(0)
	v_mfma_f32_16x16x32_bf16 v[122:125], v[220:223], v[140:143], v[122:125]
	v_mfma_f32_16x16x32_bf16 v[126:129], v[220:223], v[144:147], v[126:129]
	v_mfma_f32_16x16x32_bf16 v[106:109], v[220:223], v[148:151], v[106:109]
	v_mfma_f32_16x16x32_bf16 v[110:113], v[220:223], v[152:155], v[110:113]
	v_mfma_f32_16x16x32_bf16 v[90:93], v[224:227], v[140:143], v[90:93]
	v_mfma_f32_16x16x32_bf16 v[94:97], v[224:227], v[144:147], v[94:97]
	v_mfma_f32_16x16x32_bf16 v[74:77], v[224:227], v[148:151], v[74:77]
	v_mfma_f32_16x16x32_bf16 v[78:81], v[224:227], v[152:155], v[78:81]
	v_mfma_f32_16x16x32_bf16 v[58:61], v[228:231], v[140:143], v[58:61]
	v_mfma_f32_16x16x32_bf16 v[62:65], v[228:231], v[144:147], v[62:65]
	v_mfma_f32_16x16x32_bf16 v[42:45], v[228:231], v[148:151], v[42:45]
	v_mfma_f32_16x16x32_bf16 v[46:49], v[228:231], v[152:155], v[46:49]
	v_mfma_f32_16x16x32_bf16 v[26:29], v[238:241], v[140:143], v[26:29]
	v_mfma_f32_16x16x32_bf16 v[30:33], v[238:241], v[144:147], v[30:33]
	v_mfma_f32_16x16x32_bf16 v[10:13], v[238:241], v[148:151], v[10:13]
	v_mfma_f32_16x16x32_bf16 v[14:17], v[238:241], v[152:155], v[14:17]
	s_cmp_lt_u32 s56, s57
	s_cselect_b32 s60, 0x80, 0
	s_add_u32 s52, s52, s60
	s_addc_u32 s53, s53, 0
	s_add_u32 s54, s54, s60
	s_addc_u32 s55, s55, 0
	s_waitcnt vmcnt(0)
	s_barrier
; #define MFMA32(a, b, c) __builtin_amdgcn_mfma_f32_32x32x16_bf16((a), (b), (c), 0, 0, 0)
; DI void gemm256(const char* a_u, unsigned a_voff, size_t astep, const char* b_u, unsigned b_voff, size_t bstep, int nk, char* smem, f32x16 (&acc)[4][2]) {
;     ...
;   for (int kt = 0; kt < nk; ++kt) {
;     const int cur = kt & 1, k2 = (kt + 2 < last) ? kt + 2 : last;
;     const char* S = smem + cur * 2 * T2;
;     char* D = smem + (cur ^ 1) * 2 * T2;
;     const char* an = a_u + (size_t)k2 * 128;
;     const char* bn = b_u + (size_t)k2 * 128;
; #pragma unroll
;     for (int s = 0; s < 4; ++s) {
;       bf16x8 a[4], b[2];
; #pragma unroll
;       for (int mi = 0; mi < 4; ++mi) a[mi] = *(const bf16x8*)(S + aoff + mi * 32 * LROW + s * 32);
; #pragma unroll
;       for (int ni = 0; ni < 2; ++ni) b[ni] = *(const bf16x8*)(S + boff + ni * 32 * LROW + s * 32);
;       *(u32x4*)(D + soff + s * 64 * LROW) = ra[s];
;       *(u32x4*)(D + T2 + soff + s * 64 * LROW) = rb[s];
;       ra[s] = *(const u32x4*)(an + s * astep + a_voff);
;       rb[s] = *(const u32x4*)(bn + s * bstep + b_voff);
; #pragma unroll
;       for (int mi = 0; mi < 4; ++mi)
; #pragma unroll
;         for (int ni = 0; ni < 2; ++ni) acc[mi][ni] = MFMA32(a[mi], b[ni], acc[mi][ni]);
;     }
;     __syncthreads();
;   }
	ds_read_b128 v[196:199], v194 offset:0
	ds_read_b128 v[212:215], v160 offset:0
	ds_read_b128 v[216:219], v160 offset:2048
	ds_read_b128 v[242:245], v160 offset:4096
	ds_read_b128 v[246:249], v160 offset:6144
	ds_read_b128 v[200:203], v194 offset:4096
	ds_read_b128 v[204:207], v194 offset:8192
	ds_read_b128 v[208:211], v194 offset:12288
	s_cmp_lt_u32 s56, s57
	s_cbranch_scc1 .Lg_outproj_loop
	s_waitcnt vmcnt(0) lgkmcnt(0)
	s_nop 7
	s_nop 7
	v_permlane16_swap_b32_e32 v114, v118
	v_permlane16_swap_b32_e32 v115, v119
	v_permlane16_swap_b32_e32 v116, v120
	v_permlane16_swap_b32_e32 v117, v121
	v_permlane16_swap_b32_e32 v122, v126
	v_permlane16_swap_b32_e32 v123, v127
	v_permlane16_swap_b32_e32 v124, v128
	v_permlane16_swap_b32_e32 v125, v129
	v_permlane16_swap_b32_e32 v98, v102
	v_permlane16_swap_b32_e32 v99, v103
	v_permlane16_swap_b32_e32 v100, v104
	v_permlane16_swap_b32_e32 v101, v105
	v_permlane16_swap_b32_e32 v106, v110
	v_permlane16_swap_b32_e32 v107, v111
	v_permlane16_swap_b32_e32 v108, v112
	v_permlane16_swap_b32_e32 v109, v113
	v_permlane16_swap_b32_e32 v82, v86
	v_permlane16_swap_b32_e32 v83, v87
	v_permlane16_swap_b32_e32 v84, v88
	v_permlane16_swap_b32_e32 v85, v89
	v_permlane16_swap_b32_e32 v90, v94
	v_permlane16_swap_b32_e32 v91, v95
	v_permlane16_swap_b32_e32 v92, v96
	v_permlane16_swap_b32_e32 v93, v97
	v_permlane16_swap_b32_e32 v66, v70
	v_permlane16_swap_b32_e32 v67, v71
	v_permlane16_swap_b32_e32 v68, v72
	v_permlane16_swap_b32_e32 v69, v73
	v_permlane16_swap_b32_e32 v74, v78
	v_permlane16_swap_b32_e32 v75, v79
	v_permlane16_swap_b32_e32 v76, v80
	v_permlane16_swap_b32_e32 v77, v81
	v_permlane16_swap_b32_e32 v50, v54
	v_permlane16_swap_b32_e32 v51, v55
	v_permlane16_swap_b32_e32 v52, v56
	v_permlane16_swap_b32_e32 v53, v57
	v_permlane16_swap_b32_e32 v58, v62
	v_permlane16_swap_b32_e32 v59, v63
	v_permlane16_swap_b32_e32 v60, v64
	v_permlane16_swap_b32_e32 v61, v65
	v_permlane16_swap_b32_e32 v34, v38
	v_permlane16_swap_b32_e32 v35, v39
	v_permlane16_swap_b32_e32 v36, v40
	v_permlane16_swap_b32_e32 v37, v41
	v_permlane16_swap_b32_e32 v42, v46
	v_permlane16_swap_b32_e32 v43, v47
	v_permlane16_swap_b32_e32 v44, v48
	v_permlane16_swap_b32_e32 v45, v49
	v_permlane16_swap_b32_e32 v18, v22
	v_permlane16_swap_b32_e32 v19, v23
	v_permlane16_swap_b32_e32 v20, v24
	v_permlane16_swap_b32_e32 v21, v25
	v_permlane16_swap_b32_e32 v26, v30
	v_permlane16_swap_b32_e32 v27, v31
	v_permlane16_swap_b32_e32 v28, v32
	v_permlane16_swap_b32_e32 v29, v33
	v_permlane16_swap_b32_e32 v2, v6
	v_permlane16_swap_b32_e32 v3, v7
	v_permlane16_swap_b32_e32 v4, v8
	v_permlane16_swap_b32_e32 v5, v9
	v_permlane16_swap_b32_e32 v10, v14
	v_permlane16_swap_b32_e32 v11, v15
	v_permlane16_swap_b32_e32 v12, v16
	v_permlane16_swap_b32_e32 v13, v17
	v_permlane32_swap_b32_e32 v114, v118
	v_permlane32_swap_b32_e32 v115, v119
	v_permlane32_swap_b32_e32 v116, v120
	v_permlane32_swap_b32_e32 v117, v121
	v_permlane32_swap_b32_e32 v122, v126
	v_permlane32_swap_b32_e32 v123, v127
	v_permlane32_swap_b32_e32 v124, v128
	v_permlane32_swap_b32_e32 v125, v129
	v_permlane32_swap_b32_e32 v98, v102
	v_permlane32_swap_b32_e32 v99, v103
	v_permlane32_swap_b32_e32 v100, v104
	v_permlane32_swap_b32_e32 v101, v105
	v_permlane32_swap_b32_e32 v106, v110
	v_permlane32_swap_b32_e32 v107, v111
	v_permlane32_swap_b32_e32 v108, v112
	v_permlane32_swap_b32_e32 v109, v113
	v_permlane32_swap_b32_e32 v82, v86
	v_permlane32_swap_b32_e32 v83, v87
	v_permlane32_swap_b32_e32 v84, v88
	v_permlane32_swap_b32_e32 v85, v89
	v_permlane32_swap_b32_e32 v90, v94
	v_permlane32_swap_b32_e32 v91, v95
	v_permlane32_swap_b32_e32 v92, v96
	v_permlane32_swap_b32_e32 v93, v97
	v_permlane32_swap_b32_e32 v66, v70
	v_permlane32_swap_b32_e32 v67, v71
	v_permlane32_swap_b32_e32 v68, v72
	v_permlane32_swap_b32_e32 v69, v73
	v_permlane32_swap_b32_e32 v74, v78
	v_permlane32_swap_b32_e32 v75, v79
	v_permlane32_swap_b32_e32 v76, v80
	v_permlane32_swap_b32_e32 v77, v81
	v_permlane32_swap_b32_e32 v50, v54
	v_permlane32_swap_b32_e32 v51, v55
	v_permlane32_swap_b32_e32 v52, v56
	v_permlane32_swap_b32_e32 v53, v57
	v_permlane32_swap_b32_e32 v58, v62
	v_permlane32_swap_b32_e32 v59, v63
	v_permlane32_swap_b32_e32 v60, v64
	v_permlane32_swap_b32_e32 v61, v65
	v_permlane32_swap_b32_e32 v34, v38
	v_permlane32_swap_b32_e32 v35, v39
	v_permlane32_swap_b32_e32 v36, v40
	v_permlane32_swap_b32_e32 v37, v41
	v_permlane32_swap_b32_e32 v42, v46
	v_permlane32_swap_b32_e32 v43, v47
	v_permlane32_swap_b32_e32 v44, v48
	v_permlane32_swap_b32_e32 v45, v49
	v_permlane32_swap_b32_e32 v18, v22
	v_permlane32_swap_b32_e32 v19, v23
	v_permlane32_swap_b32_e32 v20, v24
	v_permlane32_swap_b32_e32 v21, v25
	v_permlane32_swap_b32_e32 v26, v30
	v_permlane32_swap_b32_e32 v27, v31
	v_permlane32_swap_b32_e32 v28, v32
	v_permlane32_swap_b32_e32 v29, v33
	v_permlane32_swap_b32_e32 v2, v6
	v_permlane32_swap_b32_e32 v3, v7
	v_permlane32_swap_b32_e32 v4, v8
	v_permlane32_swap_b32_e32 v5, v9
	v_permlane32_swap_b32_e32 v10, v14
	v_permlane32_swap_b32_e32 v11, v15
	v_permlane32_swap_b32_e32 v12, v16
	v_permlane32_swap_b32_e32 v13, v17
	s_nop 1
	s_branch .LBB0_925

; #define MFMA32(a, b, c) __builtin_amdgcn_mfma_f32_32x32x16_bf16((a), (b), (c), 0, 0, 0)
; DI void gemm256(const char* a_u, unsigned a_voff, size_t astep, const char* b_u, unsigned b_voff, size_t bstep, int nk, char* smem, f32x16 (&acc)[4][2]) {
;     ...
;   for (int kt = 0; kt < nk; ++kt) {
;     const int cur = kt & 1, k2 = (kt + 2 < last) ? kt + 2 : last;
;     const char* S = smem + cur * 2 * T2;
;     char* D = smem + (cur ^ 1) * 2 * T2;
;     const char* an = a_u + (size_t)k2 * 128;
;     const char* bn = b_u + (size_t)k2 * 128;
; #pragma unroll
;     for (int s = 0; s < 4; ++s) {
;       bf16x8 a[4], b[2];
; #pragma unroll
;       for (int mi = 0; mi < 4; ++mi) a[mi] = *(const bf16x8*)(S + aoff + mi * 32 * LROW + s * 32);
; #pragma unroll
;       for (int ni = 0; ni < 2; ++ni) b[ni] = *(const bf16x8*)(S + boff + ni * 32 * LROW + s * 32);
;       *(u32x4*)(D + soff + s * 64 * LROW) = ra[s];
;       *(u32x4*)(D + T2 + soff + s * 64 * LROW) = rb[s];
;       ra[s] = *(const u32x4*)(an + s * astep + a_voff);
;       rb[s] = *(const u32x4*)(bn + s * bstep + b_voff);
; #pragma unroll
;       for (int mi = 0; mi < 4; ++mi)
; #pragma unroll
;         for (int ni = 0; ni < 2; ++ni) acc[mi][ni] = MFMA32(a[mi], b[ni], acc[mi][ni]);
;     }
;     __syncthreads();
;   }
.Lg_gateup_loop:
	s_add_i32 s56, s56, 1
	s_add_u32 m0, s59, 0x8000
	s_nop 0
	global_load_lds_dwordx4 v164, s[54:55]
	global_load_lds_dwordx4 v165, s[54:55] offset:1024
	global_load_lds_dwordx4 v130, s[54:55] offset:2048
	global_load_lds_dwordx4 v131, s[54:55] offset:3072
	s_waitcnt lgkmcnt(0)
	v_mfma_f32_16x16x32_bf16 v[114:117], v[196:199], v[212:215], v[114:117]
	ds_read_b128 v[220:223], v194 offset:2048
	v_mfma_f32_16x16x32_bf16 v[118:121], v[196:199], v[216:219], v[118:121]
	ds_read_b128 v[224:227], v194 offset:6144
	v_mfma_f32_16x16x32_bf16 v[98:101], v[196:199], v[242:245], v[98:101]
	ds_read_b128 v[228:231], v194 offset:10240
	v_mfma_f32_16x16x32_bf16 v[102:105], v[196:199], v[246:249], v[102:105]
	ds_read_b128 v[238:241], v194 offset:14336
	v_mfma_f32_16x16x32_bf16 v[82:85], v[200:203], v[212:215], v[82:85]
	v_mfma_f32_16x16x32_bf16 v[86:89], v[200:203], v[216:219], v[86:89]
	v_mfma_f32_16x16x32_bf16 v[66:69], v[200:203], v[242:245], v[66:69]
	v_mfma_f32_16x16x32_bf16 v[70:73], v[200:203], v[246:249], v[70:73]
	v_mfma_f32_16x16x32_bf16 v[50:53], v[204:207], v[212:215], v[50:53]
	v_mfma_f32_16x16x32_bf16 v[54:57], v[204:207], v[216:219], v[54:57]
	v_mfma_f32_16x16x32_bf16 v[34:37], v[204:207], v[242:245], v[34:37]
	v_mfma_f32_16x16x32_bf16 v[38:41], v[204:207], v[246:249], v[38:41]
	v_mfma_f32_16x16x32_bf16 v[18:21], v[208:211], v[212:215], v[18:21]
	v_mfma_f32_16x16x32_bf16 v[22:25], v[208:211], v[216:219], v[22:25]
	v_mfma_f32_16x16x32_bf16 v[2:5], v[208:211], v[242:245], v[2:5]
	v_mfma_f32_16x16x32_bf16 v[6:9], v[208:211], v[246:249], v[6:9]
	s_add_u32 m0, s58, 0x8000
	s_nop 0
	global_load_lds_dwordx4 v164, s[52:53]
	global_load_lds_dwordx4 v165, s[52:53] offset:1024
	global_load_lds_dwordx4 v130, s[52:53] offset:2048
	global_load_lds_dwordx4 v131, s[52:53] offset:3072
	s_waitcnt lgkmcnt(0)
	v_mfma_f32_16x16x32_bf16 v[122:125], v[220:223], v[212:215], v[122:125]
	ds_read_b128 v[196:199], v195 offset:0
	v_mfma_f32_16x16x32_bf16 v[126:129], v[220:223], v[216:219], v[126:129]
	ds_read_b128 v[140:143], v161 offset:0
	v_mfma_f32_16x16x32_bf16 v[106:109], v[220:223], v[242:245], v[106:109]
	ds_read_b128 v[144:147], v161 offset:2048
	v_mfma_f32_16x16x32_bf16 v[110:113], v[220:223], v[246:249], v[110:113]
	ds_read_b128 v[148:151], v161 offset:4096
	v_mfma_f32_16x16x32_bf16 v[90:93], v[224:227], v[212:215], v[90:93]
	ds_read_b128 v[152:155], v161 offset:6144
	v_mfma_f32_16x16x32_bf16 v[94:97], v[224:227], v[216:219], v[94:97]
	ds_read_b128 v[200:203], v195 offset:4096
	v_mfma_f32_16x16x32_bf16 v[74:77], v[224:227], v[242:245], v[74:77]
	ds_read_b128 v[204:207], v195 offset:8192
	v_mfma_f32_16x16x32_bf16 v[78:81], v[224:227], v[246:249], v[78:81]
	ds_read_b128 v[208:211], v195 offset:12288
	v_mfma_f32_16x16x32_bf16 v[58:61], v[228:231], v[212:215], v[58:61]
	v_mfma_f32_16x16x32_bf16 v[62:65], v[228:231], v[216:219], v[62:65]
	v_mfma_f32_16x16x32_bf16 v[42:45], v[228:231], v[242:245], v[42:45]
	v_mfma_f32_16x16x32_bf16 v[46:49], v[228:231], v[246:249], v[46:49]
	v_mfma_f32_16x16x32_bf16 v[26:29], v[238:241], v[212:215], v[26:29]
	v_mfma_f32_16x16x32_bf16 v[30:33], v[238:241], v[216:219], v[30:33]
	v_mfma_f32_16x16x32_bf16 v[10:13], v[238:241], v[242:245], v[10:13]
	v_mfma_f32_16x16x32_bf16 v[14:17], v[238:241], v[246:249], v[14:17]
	s_waitcnt lgkmcnt(0)
	v_mfma_f32_16x16x32_bf16 v[114:117], v[196:199], v[140:143], v[114:117]
	ds_read_b128 v[220:223], v195 offset:2048
	v_mfma_f32_16x16x32_bf16 v[118:121], v[196:199], v[144:147], v[118:121]
	ds_read_b128 v[224:227], v195 offset:6144
	v_mfma_f32_16x16x32_bf16 v[98:101], v[196:199], v[148:151], v[98:101]
	ds_read_b128 v[228:231], v195 offset:10240
	v_mfma_f32_16x16x32_bf16 v[102:105], v[196:199], v[152:155], v[102:105]
	ds_read_b128 v[238:241], v195 offset:14336
	v_mfma_f32_16x16x32_bf16 v[82:85], v[200:203], v[140:143], v[82:85]
	v_mfma_f32_16x16x32_bf16 v[86:89], v[200:203], v[144:147], v[86:89]
	v_mfma_f32_16x16x32_bf16 v[66:69], v[200:203], v[148:151], v[66:69]
	v_mfma_f32_16x16x32_bf16 v[70:73], v[200:203], v[152:155], v[70:73]
	v_mfma_f32_16x16x32_bf16 v[50:53], v[204:207], v[140:143], v[50:53]
	v_mfma_f32_16x16x32_bf16 v[54:57], v[204:207], v[144:147], v[54:57]
	v_mfma_f32_16x16x32_bf16 v[34:37], v[204:207], v[148:151], v[34:37]
	v_mfma_f32_16x16x32_bf16 v[38:41], v[204:207], v[152:155], v[38:41]
	v_mfma_f32_16x16x32_bf16 v[18:21], v[208:211], v[140:143], v[18:21]
	v_mfma_f32_16x16x32_bf16 v[22:25], v[208:211], v[144:147], v[22:25]
	v_mfma_f32_16x16x32_bf16 v[2:5], v[208:211], v[148:151], v[2:5]
	v_mfma_f32_16x16x32_bf16 v[6:9], v[208:211], v[152:155], v[6:9]
	s_waitcnt lgkmcnt(0)
	v_mfma_f32_16x16x32_bf16 v[122:125], v[220:223], v[140:143], v[122:125]
	v_mfma_f32_16x16x32_bf16 v[126:129], v[220:223], v[144:147], v[126:129]
	v_mfma_f32_16x16x32_bf16 v[106:109], v[220:223], v[148:151], v[106:109]
	v_mfma_f32_16x16x32_bf16 v[110:113], v[220:223], v[152:155], v[110:113]
	v_mfma_f32_16x16x32_bf16 v[90:93], v[224:227], v[140:143], v[90:93]
	v_mfma_f32_16x16x32_bf16 v[94:97], v[224:227], v[144:147], v[94:97]
	v_mfma_f32_16x16x32_bf16 v[74:77], v[224:227], v[148:151], v[74:77]
	v_mfma_f32_16x16x32_bf16 v[78:81], v[224:227], v[152:155], v[78:81]
	v_mfma_f32_16x16x32_bf16 v[58:61], v[228:231], v[140:143], v[58:61]
	v_mfma_f32_16x16x32_bf16 v[62:65], v[228:231], v[144:147], v[62:65]
	v_mfma_f32_16x16x32_bf16 v[42:45], v[228:231], v[148:151], v[42:45]
	v_mfma_f32_16x16x32_bf16 v[46:49], v[228:231], v[152:155], v[46:49]
	v_mfma_f32_16x16x32_bf16 v[26:29], v[238:241], v[140:143], v[26:29]
	v_mfma_f32_16x16x32_bf16 v[30:33], v[238:241], v[144:147], v[30:33]
	v_mfma_f32_16x16x32_bf16 v[10:13], v[238:241], v[148:151], v[10:13]
	v_mfma_f32_16x16x32_bf16 v[14:17], v[238:241], v[152:155], v[14:17]
	s_cmp_lt_u32 s56, s57
	s_cselect_b32 s60, 0x80, 0
	s_add_u32 s52, s52, s60
	s_addc_u32 s53, s53, 0
	s_add_u32 s54, s54, s60
	s_addc_u32 s55, s55, 0
	s_cmp_eq_u32 s56, s63
	s_cselect_b32 s52, s64, s52
	s_cselect_b32 s53, s65, s53
	s_cselect_b32 s54, s66, s54
	s_cselect_b32 s55, s67, s55
	s_waitcnt vmcnt(0)
	s_barrier
; #define MFMA32(a, b, c) __builtin_amdgcn_mfma_f32_32x32x16_bf16((a), (b), (c), 0, 0, 0)
; DI void gemm256(const char* a_u, unsigned a_voff, size_t astep, const char* b_u, unsigned b_voff, size_t bstep, int nk, char* smem, f32x16 (&acc)[4][2]) {
;     ...
;   for (int kt = 0; kt < nk; ++kt) {
;     const int cur = kt & 1, k2 = (kt + 2 < last) ? kt + 2 : last;
;     const char* S = smem + cur * 2 * T2;
;     char* D = smem + (cur ^ 1) * 2 * T2;
;     const char* an = a_u + (size_t)k2 * 128;
;     const char* bn = b_u + (size_t)k2 * 128;
; #pragma unroll
;     for (int s = 0; s < 4; ++s) {
;       bf16x8 a[4], b[2];
; #pragma unroll
;       for (int mi = 0; mi < 4; ++mi) a[mi] = *(const bf16x8*)(S + aoff + mi * 32 * LROW + s * 32);
; #pragma unroll
;       for (int ni = 0; ni < 2; ++ni) b[ni] = *(const bf16x8*)(S + boff + ni * 32 * LROW + s * 32);
;       *(u32x4*)(D + soff + s * 64 * LROW) = ra[s];
;       *(u32x4*)(D + T2 + soff + s * 64 * LROW) = rb[s];
;       ra[s] = *(const u32x4*)(an + s * astep + a_voff);
;       rb[s] = *(const u32x4*)(bn + s * bstep + b_voff);
; #pragma unroll
;       for (int mi = 0; mi < 4; ++mi)
; #pragma unroll
;         for (int ni = 0; ni < 2; ++ni) acc[mi][ni] = MFMA32(a[mi], b[ni], acc[mi][ni]);
;     }
;     __syncthreads();
;   }
	ds_read_b128 v[196:199], v194 offset:32768
	ds_read_b128 v[212:215], v160 offset:32768
	ds_read_b128 v[216:219], v160 offset:34816
	ds_read_b128 v[242:245], v160 offset:36864
	ds_read_b128 v[246:249], v160 offset:38912
	ds_read_b128 v[200:203], v194 offset:36864
	ds_read_b128 v[204:207], v194 offset:40960
	ds_read_b128 v[208:211], v194 offset:45056
	s_add_i32 s56, s56, 1
	s_add_u32 m0, s59, 0x0
	s_nop 0
	global_load_lds_dwordx4 v164, s[54:55]
	global_load_lds_dwordx4 v165, s[54:55] offset:1024
	global_load_lds_dwordx4 v130, s[54:55] offset:2048
	global_load_lds_dwordx4 v131, s[54:55] offset:3072
	s_waitcnt lgkmcnt(0)
	v_mfma_f32_16x16x32_bf16 v[114:117], v[196:199], v[212:215], v[114:117]
	ds_read_b128 v[220:223], v194 offset:34816
	v_mfma_f32_16x16x32_bf16 v[118:121], v[196:199], v[216:219], v[118:121]
	ds_read_b128 v[224:227], v194 offset:38912
	v_mfma_f32_16x16x32_bf16 v[98:101], v[196:199], v[242:245], v[98:101]
	ds_read_b128 v[228:231], v194 offset:43008
	v_mfma_f32_16x16x32_bf16 v[102:105], v[196:199], v[246:249], v[102:105]
	ds_read_b128 v[238:241], v194 offset:47104
	v_mfma_f32_16x16x32_bf16 v[82:85], v[200:203], v[212:215], v[82:85]
	v_mfma_f32_16x16x32_bf16 v[86:89], v[200:203], v[216:219], v[86:89]
	v_mfma_f32_16x16x32_bf16 v[66:69], v[200:203], v[242:245], v[66:69]
	v_mfma_f32_16x16x32_bf16 v[70:73], v[200:203], v[246:249], v[70:73]
	v_mfma_f32_16x16x32_bf16 v[50:53], v[204:207], v[212:215], v[50:53]
	v_mfma_f32_16x16x32_bf16 v[54:57], v[204:207], v[216:219], v[54:57]
	v_mfma_f32_16x16x32_bf16 v[34:37], v[204:207], v[242:245], v[34:37]
	v_mfma_f32_16x16x32_bf16 v[38:41], v[204:207], v[246:249], v[38:41]
	v_mfma_f32_16x16x32_bf16 v[18:21], v[208:211], v[212:215], v[18:21]
	v_mfma_f32_16x16x32_bf16 v[22:25], v[208:211], v[216:219], v[22:25]
	v_mfma_f32_16x16x32_bf16 v[2:5], v[208:211], v[242:245], v[2:5]
	v_mfma_f32_16x16x32_bf16 v[6:9], v[208:211], v[246:249], v[6:9]
	s_add_u32 m0, s58, 0x0
	s_nop 0
	global_load_lds_dwordx4 v164, s[52:53]
	global_load_lds_dwordx4 v165, s[52:53] offset:1024
	global_load_lds_dwordx4 v130, s[52:53] offset:2048
	global_load_lds_dwordx4 v131, s[52:53] offset:3072
	s_waitcnt lgkmcnt(0)
	v_mfma_f32_16x16x32_bf16 v[122:125], v[220:223], v[212:215], v[122:125]
	ds_read_b128 v[196:199], v195 offset:32768
	v_mfma_f32_16x16x32_bf16 v[126:129], v[220:223], v[216:219], v[126:129]
	ds_read_b128 v[140:143], v161 offset:32768
	v_mfma_f32_16x16x32_bf16 v[106:109], v[220:223], v[242:245], v[106:109]
	ds_read_b128 v[144:147], v161 offset:34816
	v_mfma_f32_16x16x32_bf16 v[110:113], v[220:223], v[246:249], v[110:113]
	ds_read_b128 v[148:151], v161 offset:36864
	v_mfma_f32_16x16x32_bf16 v[90:93], v[224:227], v[212:215], v[90:93]
	ds_read_b128 v[152:155], v161 offset:38912
	v_mfma_f32_16x16x32_bf16 v[94:97], v[224:227], v[216:219], v[94:97]
	ds_read_b128 v[200:203], v195 offset:36864
	v_mfma_f32_16x16x32_bf16 v[74:77], v[224:227], v[242:245], v[74:77]
	ds_read_b128 v[204:207], v195 offset:40960
	v_mfma_f32_16x16x32_bf16 v[78:81], v[224:227], v[246:249], v[78:81]
	ds_read_b128 v[208:211], v195 offset:45056
	v_mfma_f32_16x16x32_bf16 v[58:61], v[228:231], v[212:215], v[58:61]
	v_mfma_f32_16x16x32_bf16 v[62:65], v[228:231], v[216:219], v[62:65]
	v_mfma_f32_16x16x32_bf16 v[42:45], v[228:231], v[242:245], v[42:45]
	v_mfma_f32_16x16x32_bf16 v[46:49], v[228:231], v[246:249], v[46:49]
	v_mfma_f32_16x16x32_bf16 v[26:29], v[238:241], v[212:215], v[26:29]
	v_mfma_f32_16x16x32_bf16 v[30:33], v[238:241], v[216:219], v[30:33]
	v_mfma_f32_16x16x32_bf16 v[10:13], v[238:241], v[242:245], v[10:13]
	v_mfma_f32_16x16x32_bf16 v[14:17], v[238:241], v[246:249], v[14:17]
	s_waitcnt lgkmcnt(0)
	v_mfma_f32_16x16x32_bf16 v[114:117], v[196:199], v[140:143], v[114:117]
	ds_read_b128 v[220:223], v195 offset:34816
	v_mfma_f32_16x16x32_bf16 v[118:121], v[196:199], v[144:147], v[118:121]
	ds_read_b128 v[224:227], v195 offset:38912
	v_mfma_f32_16x16x32_bf16 v[98:101], v[196:199], v[148:151], v[98:101]
	ds_read_b128 v[228:231], v195 offset:43008
	v_mfma_f32_16x16x32_bf16 v[102:105], v[196:199], v[152:155], v[102:105]
	ds_read_b128 v[238:241], v195 offset:47104
	v_mfma_f32_16x16x32_bf16 v[82:85], v[200:203], v[140:143], v[82:85]
	v_mfma_f32_16x16x32_bf16 v[86:89], v[200:203], v[144:147], v[86:89]
	v_mfma_f32_16x16x32_bf16 v[66:69], v[200:203], v[148:151], v[66:69]
	v_mfma_f32_16x16x32_bf16 v[70:73], v[200:203], v[152:155], v[70:73]
	v_mfma_f32_16x16x32_bf16 v[50:53], v[204:207], v[140:143], v[50:53]
	v_mfma_f32_16x16x32_bf16 v[54:57], v[204:207], v[144:147], v[54:57]
	v_mfma_f32_16x16x32_bf16 v[34:37], v[204:207], v[148:151], v[34:37]
	v_mfma_f32_16x16x32_bf16 v[38:41], v[204:207], v[152:155], v[38:41]
	v_mfma_f32_16x16x32_bf16 v[18:21], v[208:211], v[140:143], v[18:21]
	v_mfma_f32_16x16x32_bf16 v[22:25], v[208:211], v[144:147], v[22:25]
	v_mfma_f32_16x16x32_bf16 v[2:5], v[208:211], v[148:151], v[2:5]
	v_mfma_f32_16x16x32_bf16 v[6:9], v[208:211], v[152:155], v[6:9]
	s_waitcnt lgkmcnt(0)
	v_mfma_f32_16x16x32_bf16 v[122:125], v[220:223], v[140:143], v[122:125]
	v_mfma_f32_16x16x32_bf16 v[126:129], v[220:223], v[144:147], v[126:129]
	v_mfma_f32_16x16x32_bf16 v[106:109], v[220:223], v[148:151], v[106:109]
	v_mfma_f32_16x16x32_bf16 v[110:113], v[220:223], v[152:155], v[110:113]
	v_mfma_f32_16x16x32_bf16 v[90:93], v[224:227], v[140:143], v[90:93]
	v_mfma_f32_16x16x32_bf16 v[94:97], v[224:227], v[144:147], v[94:97]
	v_mfma_f32_16x16x32_bf16 v[74:77], v[224:227], v[148:151], v[74:77]
	v_mfma_f32_16x16x32_bf16 v[78:81], v[224:227], v[152:155], v[78:81]
	v_mfma_f32_16x16x32_bf16 v[58:61], v[228:231], v[140:143], v[58:61]
	v_mfma_f32_16x16x32_bf16 v[62:65], v[228:231], v[144:147], v[62:65]
	v_mfma_f32_16x16x32_bf16 v[42:45], v[228:231], v[148:151], v[42:45]
	v_mfma_f32_16x16x32_bf16 v[46:49], v[228:231], v[152:155], v[46:49]
	v_mfma_f32_16x16x32_bf16 v[26:29], v[238:241], v[140:143], v[26:29]
	v_mfma_f32_16x16x32_bf16 v[30:33], v[238:241], v[144:147], v[30:33]
	v_mfma_f32_16x16x32_bf16 v[10:13], v[238:241], v[148:151], v[10:13]
	v_mfma_f32_16x16x32_bf16 v[14:17], v[238:241], v[152:155], v[14:17]
	s_cmp_lt_u32 s56, s57
	s_cselect_b32 s60, 0x80, 0
	s_add_u32 s52, s52, s60
	s_addc_u32 s53, s53, 0
	s_add_u32 s54, s54, s60
	s_addc_u32 s55, s55, 0
	s_cmp_eq_u32 s56, s63
	s_cselect_b32 s52, s64, s52
	s_cselect_b32 s53, s65, s53
	s_cselect_b32 s54, s66, s54
	s_cselect_b32 s55, s67, s55
	s_waitcnt vmcnt(0)
	s_barrier
; #define MFMA32(a, b, c) __builtin_amdgcn_mfma_f32_32x32x16_bf16((a), (b), (c), 0, 0, 0)
; DI void gemm256(const char* a_u, unsigned a_voff, size_t astep, const char* b_u, unsigned b_voff, size_t bstep, int nk, char* smem, f32x16 (&acc)[4][2]) {
;     ...
;   for (int kt = 0; kt < nk; ++kt) {
;     const int cur = kt & 1, k2 = (kt + 2 < last) ? kt + 2 : last;
;     const char* S = smem + cur * 2 * T2;
;     char* D = smem + (cur ^ 1) * 2 * T2;
;     const char* an = a_u + (size_t)k2 * 128;
;     const char* bn = b_u + (size_t)k2 * 128;
; #pragma unroll
;     for (int s = 0; s < 4; ++s) {
;       bf16x8 a[4], b[2];
; #pragma unroll
;       for (int mi = 0; mi < 4; ++mi) a[mi] = *(const bf16x8*)(S + aoff + mi * 32 * LROW + s * 32);
; #pragma unroll
;       for (int ni = 0; ni < 2; ++ni) b[ni] = *(const bf16x8*)(S + boff + ni * 32 * LROW + s * 32);
;       *(u32x4*)(D + soff + s * 64 * LROW) = ra[s];
;       *(u32x4*)(D + T2 + soff + s * 64 * LROW) = rb[s];
;       ra[s] = *(const u32x4*)(an + s * astep + a_voff);
;       rb[s] = *(const u32x4*)(bn + s * bstep + b_voff);
; #pragma unroll
;       for (int mi = 0; mi < 4; ++mi)
; #pragma unroll
;         for (int ni = 0; ni < 2; ++ni) acc[mi][ni] = MFMA32(a[mi], b[ni], acc[mi][ni]);
;     }
;     __syncthreads();
;   }
	ds_read_b128 v[196:199], v194 offset:0
	ds_read_b128 v[212:215], v160 offset:0
	ds_read_b128 v[216:219], v160 offset:2048
	ds_read_b128 v[242:245], v160 offset:4096
	ds_read_b128 v[246:249], v160 offset:6144
	ds_read_b128 v[200:203], v194 offset:4096
	ds_read_b128 v[204:207], v194 offset:8192
	ds_read_b128 v[208:211], v194 offset:12288
	s_cmp_lt_u32 s56, s57
	s_cbranch_scc1 .Lg_gateup_loop
	s_waitcnt vmcnt(0) lgkmcnt(0)
	s_nop 7
	s_nop 7
	v_permlane16_swap_b32_e32 v114, v118
	v_permlane16_swap_b32_e32 v115, v119
	v_permlane16_swap_b32_e32 v116, v120
	v_permlane16_swap_b32_e32 v117, v121
	v_permlane16_swap_b32_e32 v122, v126
	v_permlane16_swap_b32_e32 v123, v127
	v_permlane16_swap_b32_e32 v124, v128
	v_permlane16_swap_b32_e32 v125, v129
	v_permlane16_swap_b32_e32 v98, v102
	v_permlane16_swap_b32_e32 v99, v103
	v_permlane16_swap_b32_e32 v100, v104
	v_permlane16_swap_b32_e32 v101, v105
	v_permlane16_swap_b32_e32 v106, v110
	v_permlane16_swap_b32_e32 v107, v111
	v_permlane16_swap_b32_e32 v108, v112
	v_permlane16_swap_b32_e32 v109, v113
	v_permlane16_swap_b32_e32 v82, v86
	v_permlane16_swap_b32_e32 v83, v87
	v_permlane16_swap_b32_e32 v84, v88
	v_permlane16_swap_b32_e32 v85, v89
	v_permlane16_swap_b32_e32 v90, v94
	v_permlane16_swap_b32_e32 v91, v95
	v_permlane16_swap_b32_e32 v92, v96
	v_permlane16_swap_b32_e32 v93, v97
	v_permlane16_swap_b32_e32 v66, v70
	v_permlane16_swap_b32_e32 v67, v71
	v_permlane16_swap_b32_e32 v68, v72
	v_permlane16_swap_b32_e32 v69, v73
	v_permlane16_swap_b32_e32 v74, v78
	v_permlane16_swap_b32_e32 v75, v79
	v_permlane16_swap_b32_e32 v76, v80
	v_permlane16_swap_b32_e32 v77, v81
	v_permlane16_swap_b32_e32 v50, v54
	v_permlane16_swap_b32_e32 v51, v55
	v_permlane16_swap_b32_e32 v52, v56
	v_permlane16_swap_b32_e32 v53, v57
	v_permlane16_swap_b32_e32 v58, v62
	v_permlane16_swap_b32_e32 v59, v63
	v_permlane16_swap_b32_e32 v60, v64
	v_permlane16_swap_b32_e32 v61, v65
	v_permlane16_swap_b32_e32 v34, v38
	v_permlane16_swap_b32_e32 v35, v39
	v_permlane16_swap_b32_e32 v36, v40
	v_permlane16_swap_b32_e32 v37, v41
	v_permlane16_swap_b32_e32 v42, v46
	v_permlane16_swap_b32_e32 v43, v47
	v_permlane16_swap_b32_e32 v44, v48
	v_permlane16_swap_b32_e32 v45, v49
	v_permlane16_swap_b32_e32 v18, v22
	v_permlane16_swap_b32_e32 v19, v23
	v_permlane16_swap_b32_e32 v20, v24
	v_permlane16_swap_b32_e32 v21, v25
	v_permlane16_swap_b32_e32 v26, v30
	v_permlane16_swap_b32_e32 v27, v31
	v_permlane16_swap_b32_e32 v28, v32
	v_permlane16_swap_b32_e32 v29, v33
	v_permlane16_swap_b32_e32 v2, v6
	v_permlane16_swap_b32_e32 v3, v7
	v_permlane16_swap_b32_e32 v4, v8
	v_permlane16_swap_b32_e32 v5, v9
	v_permlane16_swap_b32_e32 v10, v14
	v_permlane16_swap_b32_e32 v11, v15
	v_permlane16_swap_b32_e32 v12, v16
	v_permlane16_swap_b32_e32 v13, v17
	v_permlane32_swap_b32_e32 v114, v118
	v_permlane32_swap_b32_e32 v115, v119
	v_permlane32_swap_b32_e32 v116, v120
	v_permlane32_swap_b32_e32 v117, v121
	v_permlane32_swap_b32_e32 v122, v126
	v_permlane32_swap_b32_e32 v123, v127
	v_permlane32_swap_b32_e32 v124, v128
	v_permlane32_swap_b32_e32 v125, v129
	v_permlane32_swap_b32_e32 v98, v102
	v_permlane32_swap_b32_e32 v99, v103
	v_permlane32_swap_b32_e32 v100, v104
	v_permlane32_swap_b32_e32 v101, v105
	v_permlane32_swap_b32_e32 v106, v110
	v_permlane32_swap_b32_e32 v107, v111
	v_permlane32_swap_b32_e32 v108, v112
	v_permlane32_swap_b32_e32 v109, v113
	v_permlane32_swap_b32_e32 v82, v86
	v_permlane32_swap_b32_e32 v83, v87
	v_permlane32_swap_b32_e32 v84, v88
	v_permlane32_swap_b32_e32 v85, v89
	v_permlane32_swap_b32_e32 v90, v94
	v_permlane32_swap_b32_e32 v91, v95
	v_permlane32_swap_b32_e32 v92, v96
	v_permlane32_swap_b32_e32 v93, v97
	v_permlane32_swap_b32_e32 v66, v70
	v_permlane32_swap_b32_e32 v67, v71
	v_permlane32_swap_b32_e32 v68, v72
	v_permlane32_swap_b32_e32 v69, v73
	v_permlane32_swap_b32_e32 v74, v78
	v_permlane32_swap_b32_e32 v75, v79
	v_permlane32_swap_b32_e32 v76, v80
	v_permlane32_swap_b32_e32 v77, v81
	v_permlane32_swap_b32_e32 v50, v54
	v_permlane32_swap_b32_e32 v51, v55
	v_permlane32_swap_b32_e32 v52, v56
	v_permlane32_swap_b32_e32 v53, v57
	v_permlane32_swap_b32_e32 v58, v62
	v_permlane32_swap_b32_e32 v59, v63
	v_permlane32_swap_b32_e32 v60, v64
	v_permlane32_swap_b32_e32 v61, v65
	v_permlane32_swap_b32_e32 v34, v38
	v_permlane32_swap_b32_e32 v35, v39
	v_permlane32_swap_b32_e32 v36, v40
	v_permlane32_swap_b32_e32 v37, v41
	v_permlane32_swap_b32_e32 v42, v46
	v_permlane32_swap_b32_e32 v43, v47
	v_permlane32_swap_b32_e32 v44, v48
	v_permlane32_swap_b32_e32 v45, v49
	v_permlane32_swap_b32_e32 v18, v22
	v_permlane32_swap_b32_e32 v19, v23
	v_permlane32_swap_b32_e32 v20, v24
	v_permlane32_swap_b32_e32 v21, v25
	v_permlane32_swap_b32_e32 v26, v30
	v_permlane32_swap_b32_e32 v27, v31
	v_permlane32_swap_b32_e32 v28, v32
	v_permlane32_swap_b32_e32 v29, v33
	v_permlane32_swap_b32_e32 v2, v6
	v_permlane32_swap_b32_e32 v3, v7
	v_permlane32_swap_b32_e32 v4, v8
	v_permlane32_swap_b32_e32 v5, v9
	v_permlane32_swap_b32_e32 v10, v14
	v_permlane32_swap_b32_e32 v11, v15
	v_permlane32_swap_b32_e32 v12, v16
	v_permlane32_swap_b32_e32 v13, v17
	s_nop 1
	s_branch .LBB0_1568
